# code placement: every 32-MFMA segment of the six K-loops starts on an 8-byte boundary (s_nop 0 pad in the preceding load segment), on top of the split-barrier version
# baseline (speedup 1.0000x reference)
.LBB0_350:
	s_add_u32 s46, s30, 0x1fc000
	s_addc_u32 s47, s31, 0
	s_and_b64 s[36:37], exec, s[36:37]
	s_cselect_b32 s46, s78, s46
	s_cselect_b32 s47, s19, s47
	s_add_u32 s36, s46, 0x200000
	s_addc_u32 s37, s47, 0
	s_add_i32 s79, 0, 0x10000
	s_add_i32 s86, 0, 0x14000
	ds_read_b128 v[148:151], v145
	ds_read_b128 v[152:155], v145 offset:1024
	ds_read_b128 v[156:159], v145 offset:2048
	ds_read_b128 v[160:163], v145 offset:3072
	ds_read_b128 v[164:167], v145 offset:16384
	ds_read_b128 v[168:171], v145 offset:17408
	ds_read_b128 v[172:175], v145 offset:18432
	ds_read_b128 v[176:179], v145 offset:19456
	s_add_i32 m0, s61, 0xc000
	ds_read_b128 v[180:183], v146
	ds_read_b128 v[184:187], v146 offset:1024
	ds_read_b128 v[188:191], v146 offset:2048
	ds_read_b128 v[192:195], v146 offset:3072
	ds_read_b128 v[200:203], v146 offset:4096
	ds_read_b128 v[204:207], v146 offset:5120
	ds_read_b128 v[208:211], v146 offset:6144
	ds_read_b128 v[222:225], v146 offset:7168
	global_load_lds_dwordx4 v140, s[30:31]
	s_add_i32 m0, s61, 0xe000
	s_nop 0
	global_load_lds_dwordx4 v142, s[30:31]
	s_waitcnt vmcnt(8)
	s_waitcnt lgkmcnt(0)
	s_barrier
	v_mfma_f32_16x16x32_bf16 v[128:131], v[148:151], v[180:183], v[128:131]
	v_mfma_f32_16x16x32_bf16 v[124:127], v[156:159], v[180:183], v[124:127]
	v_mfma_f32_16x16x32_bf16 v[112:115], v[148:151], v[188:191], v[112:115]
	v_mfma_f32_16x16x32_bf16 v[108:111], v[156:159], v[188:191], v[108:111]
	v_mfma_f32_16x16x32_bf16 v[96:99], v[148:151], v[200:203], v[96:99]
	v_mfma_f32_16x16x32_bf16 v[92:95], v[156:159], v[200:203], v[92:95]
	v_mfma_f32_16x16x32_bf16 v[80:83], v[148:151], v[208:211], v[80:83]
	v_mfma_f32_16x16x32_bf16 v[76:79], v[156:159], v[208:211], v[76:79]
	v_mfma_f32_16x16x32_bf16 v[128:131], v[152:155], v[184:187], v[128:131]
	v_mfma_f32_16x16x32_bf16 v[124:127], v[160:163], v[184:187], v[124:127]
	v_mfma_f32_16x16x32_bf16 v[112:115], v[152:155], v[192:195], v[112:115]
	v_mfma_f32_16x16x32_bf16 v[108:111], v[160:163], v[192:195], v[108:111]
	v_mfma_f32_16x16x32_bf16 v[96:99], v[152:155], v[204:207], v[96:99]
	v_mfma_f32_16x16x32_bf16 v[92:95], v[160:163], v[204:207], v[92:95]
	v_mfma_f32_16x16x32_bf16 v[80:83], v[152:155], v[222:225], v[80:83]
	v_mfma_f32_16x16x32_bf16 v[76:79], v[160:163], v[222:225], v[76:79]
	v_mfma_f32_16x16x32_bf16 v[120:123], v[164:167], v[180:183], v[120:123]
	v_mfma_f32_16x16x32_bf16 v[116:119], v[172:175], v[180:183], v[116:119]
	v_mfma_f32_16x16x32_bf16 v[104:107], v[164:167], v[188:191], v[104:107]
	v_mfma_f32_16x16x32_bf16 v[100:103], v[172:175], v[188:191], v[100:103]
	v_mfma_f32_16x16x32_bf16 v[88:91], v[164:167], v[200:203], v[88:91]
	v_mfma_f32_16x16x32_bf16 v[84:87], v[172:175], v[200:203], v[84:87]
	v_mfma_f32_16x16x32_bf16 v[72:75], v[164:167], v[208:211], v[72:75]
	v_mfma_f32_16x16x32_bf16 v[68:71], v[172:175], v[208:211], v[68:71]
	v_mfma_f32_16x16x32_bf16 v[120:123], v[168:171], v[184:187], v[120:123]
	v_mfma_f32_16x16x32_bf16 v[116:119], v[176:179], v[184:187], v[116:119]
	v_mfma_f32_16x16x32_bf16 v[104:107], v[168:171], v[192:195], v[104:107]
	v_mfma_f32_16x16x32_bf16 v[100:103], v[176:179], v[192:195], v[100:103]
	v_mfma_f32_16x16x32_bf16 v[88:91], v[168:171], v[204:207], v[88:91]
	v_mfma_f32_16x16x32_bf16 v[84:87], v[176:179], v[204:207], v[84:87]
	v_mfma_f32_16x16x32_bf16 v[72:75], v[168:171], v[222:225], v[72:75]
	v_mfma_f32_16x16x32_bf16 v[68:71], v[176:179], v[222:225], v[68:71]
	s_barrier
	s_add_i32 s79, s79, s58
	s_mov_b32 m0, s79
	ds_read_b128 v[180:183], v146 offset:16384
	ds_read_b128 v[184:187], v146 offset:17408
	ds_read_b128 v[188:191], v146 offset:18432
	ds_read_b128 v[192:195], v146 offset:19456
	ds_read_b128 v[200:203], v146 offset:20480
	ds_read_b128 v[204:207], v146 offset:21504
	ds_read_b128 v[208:211], v146 offset:22528
	ds_read_b128 v[222:225], v146 offset:23552
	global_load_lds_dwordx4 v136, s[44:45]
	s_add_i32 m0, s79, 0x2000
	s_add_u32 s82, s44, 0x4000
	s_addc_u32 s83, s45, 0
	s_add_i32 s79, s86, s58
	global_load_lds_dwordx4 v132, s[44:45]
	s_mov_b32 m0, s79
	s_nop 0
	global_load_lds_dwordx4 v136, s[82:83]
	s_add_i32 m0, s79, 0x2000
	s_nop 0
	global_load_lds_dwordx4 v132, s[82:83]
	s_mov_b32 m0, s61
	s_nop 0
	global_load_lds_dwordx4 v138, s[46:47]
	s_mov_b32 m0, s66
	s_nop 0
	global_load_lds_dwordx4 v134, s[46:47]
	s_waitcnt vmcnt(8)
	s_waitcnt lgkmcnt(0)
	s_nop 0
	s_barrier
	v_mfma_f32_16x16x32_bf16 v[64:67], v[148:151], v[180:183], v[64:67]
	v_mfma_f32_16x16x32_bf16 v[60:63], v[156:159], v[180:183], v[60:63]
	v_mfma_f32_16x16x32_bf16 v[48:51], v[148:151], v[188:191], v[48:51]
	v_mfma_f32_16x16x32_bf16 v[44:47], v[156:159], v[188:191], v[44:47]
	v_mfma_f32_16x16x32_bf16 v[32:35], v[148:151], v[200:203], v[32:35]
	v_mfma_f32_16x16x32_bf16 v[28:31], v[156:159], v[200:203], v[28:31]
	v_mfma_f32_16x16x32_bf16 v[12:15], v[148:151], v[208:211], v[12:15]
	v_mfma_f32_16x16x32_bf16 v[16:19], v[156:159], v[208:211], v[16:19]
	v_mfma_f32_16x16x32_bf16 v[64:67], v[152:155], v[184:187], v[64:67]
	v_mfma_f32_16x16x32_bf16 v[60:63], v[160:163], v[184:187], v[60:63]
	v_mfma_f32_16x16x32_bf16 v[48:51], v[152:155], v[192:195], v[48:51]
	v_mfma_f32_16x16x32_bf16 v[44:47], v[160:163], v[192:195], v[44:47]
	v_mfma_f32_16x16x32_bf16 v[32:35], v[152:155], v[204:207], v[32:35]
	v_mfma_f32_16x16x32_bf16 v[28:31], v[160:163], v[204:207], v[28:31]
	v_mfma_f32_16x16x32_bf16 v[12:15], v[152:155], v[222:225], v[12:15]
	v_mfma_f32_16x16x32_bf16 v[16:19], v[160:163], v[222:225], v[16:19]
	v_mfma_f32_16x16x32_bf16 v[56:59], v[164:167], v[180:183], v[56:59]
	v_mfma_f32_16x16x32_bf16 v[52:55], v[172:175], v[180:183], v[52:55]
	v_mfma_f32_16x16x32_bf16 v[40:43], v[164:167], v[188:191], v[40:43]
	v_mfma_f32_16x16x32_bf16 v[36:39], v[172:175], v[188:191], v[36:39]
	v_mfma_f32_16x16x32_bf16 v[24:27], v[164:167], v[200:203], v[24:27]
	v_mfma_f32_16x16x32_bf16 v[20:23], v[172:175], v[200:203], v[20:23]
	v_mfma_f32_16x16x32_bf16 v[4:7], v[164:167], v[208:211], v[4:7]
	v_mfma_f32_16x16x32_bf16 v[8:11], v[172:175], v[208:211], v[8:11]
	v_mfma_f32_16x16x32_bf16 v[56:59], v[168:171], v[184:187], v[56:59]
	v_mfma_f32_16x16x32_bf16 v[52:55], v[176:179], v[184:187], v[52:55]
	v_mfma_f32_16x16x32_bf16 v[40:43], v[168:171], v[192:195], v[40:43]
	v_mfma_f32_16x16x32_bf16 v[36:39], v[176:179], v[192:195], v[36:39]
	v_mfma_f32_16x16x32_bf16 v[24:27], v[168:171], v[204:207], v[24:27]
	v_mfma_f32_16x16x32_bf16 v[20:23], v[176:179], v[204:207], v[20:23]
	v_mfma_f32_16x16x32_bf16 v[4:7], v[168:171], v[222:225], v[4:7]
	v_mfma_f32_16x16x32_bf16 v[8:11], v[176:179], v[222:225], v[8:11]
	s_barrier
	s_add_i32 s79, 0, 0x18000
	s_add_i32 s82, 0, 0x1c000
	ds_read_b128 v[148:151], v145 offset:32768
	ds_read_b128 v[152:155], v145 offset:33792
	ds_read_b128 v[156:159], v145 offset:34816
	ds_read_b128 v[160:163], v145 offset:35840
	ds_read_b128 v[164:167], v145 offset:49152
	ds_read_b128 v[168:171], v145 offset:50176
	ds_read_b128 v[172:175], v145 offset:51200
	ds_read_b128 v[176:179], v145 offset:52224
	s_add_u32 s46, s46, 0x4000
	s_addc_u32 s47, s47, 0
	s_mov_b32 m0, s67
	ds_read_b128 v[180:183], v146 offset:32768
	ds_read_b128 v[184:187], v146 offset:33792
	ds_read_b128 v[188:191], v146 offset:34816
	ds_read_b128 v[192:195], v146 offset:35840
	ds_read_b128 v[200:203], v146 offset:36864
	ds_read_b128 v[204:207], v146 offset:37888
	ds_read_b128 v[208:211], v146 offset:38912
	ds_read_b128 v[222:225], v146 offset:39936
	global_load_lds_dwordx4 v138, s[46:47]
	s_mov_b32 m0, s70
	s_nop 0
	global_load_lds_dwordx4 v134, s[46:47]
	s_waitcnt vmcnt(8)
	s_waitcnt lgkmcnt(0)
	s_barrier
	v_mfma_f32_16x16x32_bf16 v[128:131], v[148:151], v[180:183], v[128:131]
	v_mfma_f32_16x16x32_bf16 v[124:127], v[156:159], v[180:183], v[124:127]
	v_mfma_f32_16x16x32_bf16 v[112:115], v[148:151], v[188:191], v[112:115]
	v_mfma_f32_16x16x32_bf16 v[108:111], v[156:159], v[188:191], v[108:111]
	v_mfma_f32_16x16x32_bf16 v[96:99], v[148:151], v[200:203], v[96:99]
	v_mfma_f32_16x16x32_bf16 v[92:95], v[156:159], v[200:203], v[92:95]
	v_mfma_f32_16x16x32_bf16 v[80:83], v[148:151], v[208:211], v[80:83]
	v_mfma_f32_16x16x32_bf16 v[76:79], v[156:159], v[208:211], v[76:79]
	v_mfma_f32_16x16x32_bf16 v[128:131], v[152:155], v[184:187], v[128:131]
	v_mfma_f32_16x16x32_bf16 v[124:127], v[160:163], v[184:187], v[124:127]
	v_mfma_f32_16x16x32_bf16 v[112:115], v[152:155], v[192:195], v[112:115]
	v_mfma_f32_16x16x32_bf16 v[108:111], v[160:163], v[192:195], v[108:111]
	v_mfma_f32_16x16x32_bf16 v[96:99], v[152:155], v[204:207], v[96:99]
	v_mfma_f32_16x16x32_bf16 v[92:95], v[160:163], v[204:207], v[92:95]
	v_mfma_f32_16x16x32_bf16 v[80:83], v[152:155], v[222:225], v[80:83]
	v_mfma_f32_16x16x32_bf16 v[76:79], v[160:163], v[222:225], v[76:79]
	v_mfma_f32_16x16x32_bf16 v[120:123], v[164:167], v[180:183], v[120:123]
	v_mfma_f32_16x16x32_bf16 v[116:119], v[172:175], v[180:183], v[116:119]
	v_mfma_f32_16x16x32_bf16 v[104:107], v[164:167], v[188:191], v[104:107]
	v_mfma_f32_16x16x32_bf16 v[100:103], v[172:175], v[188:191], v[100:103]
	v_mfma_f32_16x16x32_bf16 v[88:91], v[164:167], v[200:203], v[88:91]
	v_mfma_f32_16x16x32_bf16 v[84:87], v[172:175], v[200:203], v[84:87]
	v_mfma_f32_16x16x32_bf16 v[72:75], v[164:167], v[208:211], v[72:75]
	v_mfma_f32_16x16x32_bf16 v[68:71], v[172:175], v[208:211], v[68:71]
	v_mfma_f32_16x16x32_bf16 v[120:123], v[168:171], v[184:187], v[120:123]
	v_mfma_f32_16x16x32_bf16 v[116:119], v[176:179], v[184:187], v[116:119]
	v_mfma_f32_16x16x32_bf16 v[104:107], v[168:171], v[192:195], v[104:107]
	v_mfma_f32_16x16x32_bf16 v[100:103], v[176:179], v[192:195], v[100:103]
	v_mfma_f32_16x16x32_bf16 v[88:91], v[168:171], v[204:207], v[88:91]
	v_mfma_f32_16x16x32_bf16 v[84:87], v[176:179], v[204:207], v[84:87]
	v_mfma_f32_16x16x32_bf16 v[72:75], v[168:171], v[222:225], v[72:75]
	v_mfma_f32_16x16x32_bf16 v[68:71], v[176:179], v[222:225], v[68:71]
	s_barrier
	s_add_u32 s46, s44, 0x160000
	s_addc_u32 s47, s45, 0
	s_add_i32 s79, s79, s58
	s_mov_b32 m0, s79
	ds_read_b128 v[180:183], v146 offset:49152
	ds_read_b128 v[184:187], v146 offset:50176
	ds_read_b128 v[188:191], v146 offset:51200
	ds_read_b128 v[192:195], v146 offset:52224
	ds_read_b128 v[200:203], v146 offset:53248
	ds_read_b128 v[204:207], v146 offset:54272
	ds_read_b128 v[208:211], v146 offset:55296
	ds_read_b128 v[222:225], v146 offset:56320
	global_load_lds_dwordx4 v136, s[46:47]
	s_add_i32 m0, s79, 0x2000
	s_add_u32 s44, s44, 0x164000
	s_addc_u32 s45, s45, 0
	global_load_lds_dwordx4 v132, s[46:47]
	s_add_i32 s46, s82, s58
	s_mov_b32 m0, s46
	s_nop 0
	global_load_lds_dwordx4 v136, s[44:45]
	s_add_i32 m0, s46, 0x2000
	s_nop 0
	global_load_lds_dwordx4 v132, s[44:45]
	s_mov_b32 m0, s75
	s_nop 0
	global_load_lds_dwordx4 v138, s[36:37]
	s_mov_b32 m0, s76
	s_nop 0
	global_load_lds_dwordx4 v134, s[36:37]
	s_waitcnt vmcnt(8)
	s_waitcnt lgkmcnt(0)
	s_barrier
	v_mfma_f32_16x16x32_bf16 v[64:67], v[148:151], v[180:183], v[64:67]
	v_mfma_f32_16x16x32_bf16 v[60:63], v[156:159], v[180:183], v[60:63]
	v_mfma_f32_16x16x32_bf16 v[48:51], v[148:151], v[188:191], v[48:51]
	v_mfma_f32_16x16x32_bf16 v[44:47], v[156:159], v[188:191], v[44:47]
	v_mfma_f32_16x16x32_bf16 v[32:35], v[148:151], v[200:203], v[32:35]
	v_mfma_f32_16x16x32_bf16 v[28:31], v[156:159], v[200:203], v[28:31]
	v_mfma_f32_16x16x32_bf16 v[12:15], v[148:151], v[208:211], v[12:15]
	v_mfma_f32_16x16x32_bf16 v[16:19], v[156:159], v[208:211], v[16:19]
	v_mfma_f32_16x16x32_bf16 v[64:67], v[152:155], v[184:187], v[64:67]
	v_mfma_f32_16x16x32_bf16 v[60:63], v[160:163], v[184:187], v[60:63]
	v_mfma_f32_16x16x32_bf16 v[48:51], v[152:155], v[192:195], v[48:51]
	v_mfma_f32_16x16x32_bf16 v[44:47], v[160:163], v[192:195], v[44:47]
	v_mfma_f32_16x16x32_bf16 v[32:35], v[152:155], v[204:207], v[32:35]
	v_mfma_f32_16x16x32_bf16 v[28:31], v[160:163], v[204:207], v[28:31]
	v_mfma_f32_16x16x32_bf16 v[12:15], v[152:155], v[222:225], v[12:15]
	v_mfma_f32_16x16x32_bf16 v[16:19], v[160:163], v[222:225], v[16:19]
	v_mfma_f32_16x16x32_bf16 v[56:59], v[164:167], v[180:183], v[56:59]
	v_mfma_f32_16x16x32_bf16 v[52:55], v[172:175], v[180:183], v[52:55]
	v_mfma_f32_16x16x32_bf16 v[40:43], v[164:167], v[188:191], v[40:43]
	v_mfma_f32_16x16x32_bf16 v[36:39], v[172:175], v[188:191], v[36:39]
	v_mfma_f32_16x16x32_bf16 v[24:27], v[164:167], v[200:203], v[24:27]
	v_mfma_f32_16x16x32_bf16 v[20:23], v[172:175], v[200:203], v[20:23]
	v_mfma_f32_16x16x32_bf16 v[4:7], v[164:167], v[208:211], v[4:7]
	v_mfma_f32_16x16x32_bf16 v[8:11], v[172:175], v[208:211], v[8:11]
	v_mfma_f32_16x16x32_bf16 v[56:59], v[168:171], v[184:187], v[56:59]
	v_mfma_f32_16x16x32_bf16 v[52:55], v[176:179], v[184:187], v[52:55]
	v_mfma_f32_16x16x32_bf16 v[40:43], v[168:171], v[192:195], v[40:43]
	v_mfma_f32_16x16x32_bf16 v[36:39], v[176:179], v[192:195], v[36:39]
	v_mfma_f32_16x16x32_bf16 v[24:27], v[168:171], v[204:207], v[24:27]
	v_mfma_f32_16x16x32_bf16 v[20:23], v[176:179], v[204:207], v[20:23]
	v_mfma_f32_16x16x32_bf16 v[4:7], v[168:171], v[222:225], v[4:7]
	v_mfma_f32_16x16x32_bf16 v[8:11], v[176:179], v[222:225], v[8:11]
	s_barrier
	s_add_i32 s15, s15, 2
	s_add_u32 s28, s28, 0x2c0000
	s_addc_u32 s29, s29, 0
	s_add_u32 s30, s30, 0x400000
	s_addc_u32 s31, s31, 0
	s_cmp_gt_u32 s15, 29
	s_cbranch_scc1 .LBB0_353

.LBB0_433:
	s_add_u32 s30, s28, 0x1fc000
	s_addc_u32 s31, s29, 0
	s_cmpk_eq_i32 s58, 0x54
	s_cselect_b32 s44, s34, s30
	s_cselect_b32 s45, s21, s31
	s_cselect_b32 s37, s19, s49
	s_cselect_b32 s36, s35, s48
	s_add_u32 s30, s44, 0x200000
	s_addc_u32 s31, s45, 0
	s_add_i32 s59, 0, 0x10000
	s_add_i32 s61, 0, 0x14000
	ds_read_b128 v[132:135], v203
	ds_read_b128 v[136:139], v203 offset:1024
	ds_read_b128 v[140:143], v203 offset:2048
	ds_read_b128 v[144:147], v203 offset:3072
	ds_read_b128 v[148:151], v203 offset:16384
	ds_read_b128 v[152:155], v203 offset:17408
	ds_read_b128 v[156:159], v203 offset:18432
	ds_read_b128 v[170:173], v203 offset:19456
	s_add_i32 m0, s76, 0xc000
	ds_read_b128 v[174:177], v205
	ds_read_b128 v[178:181], v205 offset:1024
	ds_read_b128 v[182:185], v205 offset:2048
	ds_read_b128 v[186:189], v205 offset:3072
	ds_read_b128 v[190:193], v205 offset:4096
	ds_read_b128 v[206:209], v205 offset:5120
	ds_read_b128 v[210:213], v205 offset:6144
	ds_read_b128 v[222:225], v205 offset:7168
	global_load_lds_dwordx4 v166, s[28:29]
	s_add_i32 m0, s76, 0xe000
	s_nop 0
	global_load_lds_dwordx4 v168, s[28:29]
	s_waitcnt vmcnt(8)
	s_waitcnt lgkmcnt(0)
	s_nop 0
	s_barrier
	v_mfma_f32_16x16x32_bf16 v[128:131], v[132:135], v[174:177], v[128:131]
	v_mfma_f32_16x16x32_bf16 v[124:127], v[140:143], v[174:177], v[124:127]
	v_mfma_f32_16x16x32_bf16 v[112:115], v[132:135], v[182:185], v[112:115]
	v_mfma_f32_16x16x32_bf16 v[108:111], v[140:143], v[182:185], v[108:111]
	v_mfma_f32_16x16x32_bf16 v[96:99], v[132:135], v[190:193], v[96:99]
	v_mfma_f32_16x16x32_bf16 v[92:95], v[140:143], v[190:193], v[92:95]
	v_mfma_f32_16x16x32_bf16 v[88:91], v[132:135], v[210:213], v[88:91]
	v_mfma_f32_16x16x32_bf16 v[80:83], v[140:143], v[210:213], v[80:83]
	v_mfma_f32_16x16x32_bf16 v[128:131], v[136:139], v[178:181], v[128:131]
	v_mfma_f32_16x16x32_bf16 v[124:127], v[144:147], v[178:181], v[124:127]
	v_mfma_f32_16x16x32_bf16 v[112:115], v[136:139], v[186:189], v[112:115]
	v_mfma_f32_16x16x32_bf16 v[108:111], v[144:147], v[186:189], v[108:111]
	v_mfma_f32_16x16x32_bf16 v[96:99], v[136:139], v[206:209], v[96:99]
	v_mfma_f32_16x16x32_bf16 v[92:95], v[144:147], v[206:209], v[92:95]
	v_mfma_f32_16x16x32_bf16 v[88:91], v[136:139], v[222:225], v[88:91]
	v_mfma_f32_16x16x32_bf16 v[80:83], v[144:147], v[222:225], v[80:83]
	v_mfma_f32_16x16x32_bf16 v[120:123], v[148:151], v[174:177], v[120:123]
	v_mfma_f32_16x16x32_bf16 v[116:119], v[156:159], v[174:177], v[116:119]
	v_mfma_f32_16x16x32_bf16 v[104:107], v[148:151], v[182:185], v[104:107]
	v_mfma_f32_16x16x32_bf16 v[100:103], v[156:159], v[182:185], v[100:103]
	v_mfma_f32_16x16x32_bf16 v[84:87], v[148:151], v[190:193], v[84:87]
	v_mfma_f32_16x16x32_bf16 v[76:79], v[156:159], v[190:193], v[76:79]
	v_mfma_f32_16x16x32_bf16 v[72:75], v[148:151], v[210:213], v[72:75]
	v_mfma_f32_16x16x32_bf16 v[68:71], v[156:159], v[210:213], v[68:71]
	v_mfma_f32_16x16x32_bf16 v[120:123], v[152:155], v[178:181], v[120:123]
	v_mfma_f32_16x16x32_bf16 v[116:119], v[170:173], v[178:181], v[116:119]
	v_mfma_f32_16x16x32_bf16 v[104:107], v[152:155], v[186:189], v[104:107]
	v_mfma_f32_16x16x32_bf16 v[100:103], v[170:173], v[186:189], v[100:103]
	v_mfma_f32_16x16x32_bf16 v[84:87], v[152:155], v[206:209], v[84:87]
	v_mfma_f32_16x16x32_bf16 v[76:79], v[170:173], v[206:209], v[76:79]
	v_mfma_f32_16x16x32_bf16 v[72:75], v[152:155], v[222:225], v[72:75]
	v_mfma_f32_16x16x32_bf16 v[68:71], v[170:173], v[222:225], v[68:71]
	s_barrier
	s_add_i32 s59, s59, s75
	s_mov_b32 m0, s59
	ds_read_b128 v[174:177], v205 offset:16384
	ds_read_b128 v[178:181], v205 offset:17408
	ds_read_b128 v[182:185], v205 offset:18432
	ds_read_b128 v[186:189], v205 offset:19456
	ds_read_b128 v[190:193], v205 offset:20480
	ds_read_b128 v[206:209], v205 offset:21504
	ds_read_b128 v[210:213], v205 offset:22528
	ds_read_b128 v[222:225], v205 offset:23552
	global_load_lds_dwordx4 v2, s[36:37]
	s_add_i32 m0, s59, 0x2000
	s_add_u32 s66, s36, 0x4000
	s_addc_u32 s67, s37, 0
	s_add_i32 s59, s61, s75
	global_load_lds_dwordx4 v164, s[36:37]
	s_mov_b32 m0, s59
	s_nop 0
	global_load_lds_dwordx4 v2, s[66:67]
	s_add_i32 m0, s59, 0x2000
	s_nop 0
	global_load_lds_dwordx4 v164, s[66:67]
	s_mov_b32 m0, s76
	s_nop 0
	global_load_lds_dwordx4 v160, s[44:45]
	s_mov_b32 m0, s77
	s_nop 0
	global_load_lds_dwordx4 v162, s[44:45]
	s_waitcnt vmcnt(8)
	s_waitcnt lgkmcnt(0)
	s_nop 0
	s_barrier
	v_mfma_f32_16x16x32_bf16 v[64:67], v[132:135], v[174:177], v[64:67]
	v_mfma_f32_16x16x32_bf16 v[60:63], v[140:143], v[174:177], v[60:63]
	v_mfma_f32_16x16x32_bf16 v[48:51], v[132:135], v[182:185], v[48:51]
	v_mfma_f32_16x16x32_bf16 v[44:47], v[140:143], v[182:185], v[44:47]
	v_mfma_f32_16x16x32_bf16 v[32:35], v[132:135], v[190:193], v[32:35]
	v_mfma_f32_16x16x32_bf16 v[28:31], v[140:143], v[190:193], v[28:31]
	v_mfma_f32_16x16x32_bf16 v[16:19], v[132:135], v[210:213], v[16:19]
	v_mfma_f32_16x16x32_bf16 v[12:15], v[140:143], v[210:213], v[12:15]
	v_mfma_f32_16x16x32_bf16 v[64:67], v[136:139], v[178:181], v[64:67]
	v_mfma_f32_16x16x32_bf16 v[60:63], v[144:147], v[178:181], v[60:63]
	v_mfma_f32_16x16x32_bf16 v[48:51], v[136:139], v[186:189], v[48:51]
	v_mfma_f32_16x16x32_bf16 v[44:47], v[144:147], v[186:189], v[44:47]
	v_mfma_f32_16x16x32_bf16 v[32:35], v[136:139], v[206:209], v[32:35]
	v_mfma_f32_16x16x32_bf16 v[28:31], v[144:147], v[206:209], v[28:31]
	v_mfma_f32_16x16x32_bf16 v[16:19], v[136:139], v[222:225], v[16:19]
	v_mfma_f32_16x16x32_bf16 v[12:15], v[144:147], v[222:225], v[12:15]
	v_mfma_f32_16x16x32_bf16 v[56:59], v[148:151], v[174:177], v[56:59]
	v_mfma_f32_16x16x32_bf16 v[52:55], v[156:159], v[174:177], v[52:55]
	v_mfma_f32_16x16x32_bf16 v[40:43], v[148:151], v[182:185], v[40:43]
	v_mfma_f32_16x16x32_bf16 v[36:39], v[156:159], v[182:185], v[36:39]
	v_mfma_f32_16x16x32_bf16 v[24:27], v[148:151], v[190:193], v[24:27]
	v_mfma_f32_16x16x32_bf16 v[20:23], v[156:159], v[190:193], v[20:23]
	v_mfma_f32_16x16x32_bf16 v[8:11], v[148:151], v[210:213], v[8:11]
	v_mfma_f32_16x16x32_bf16 v[4:7], v[156:159], v[210:213], v[4:7]
	v_mfma_f32_16x16x32_bf16 v[56:59], v[152:155], v[178:181], v[56:59]
	v_mfma_f32_16x16x32_bf16 v[52:55], v[170:173], v[178:181], v[52:55]
	v_mfma_f32_16x16x32_bf16 v[40:43], v[152:155], v[186:189], v[40:43]
	v_mfma_f32_16x16x32_bf16 v[36:39], v[170:173], v[186:189], v[36:39]
	v_mfma_f32_16x16x32_bf16 v[24:27], v[152:155], v[206:209], v[24:27]
	v_mfma_f32_16x16x32_bf16 v[20:23], v[170:173], v[206:209], v[20:23]
	v_mfma_f32_16x16x32_bf16 v[8:11], v[152:155], v[222:225], v[8:11]
	v_mfma_f32_16x16x32_bf16 v[4:7], v[170:173], v[222:225], v[4:7]
	s_barrier
	s_add_i32 s59, 0, 0x18000
	s_add_i32 s61, 0, 0x1c000
	ds_read_b128 v[132:135], v203 offset:32768
	ds_read_b128 v[136:139], v203 offset:33792
	ds_read_b128 v[140:143], v203 offset:34816
	ds_read_b128 v[144:147], v203 offset:35840
	ds_read_b128 v[148:151], v203 offset:49152
	ds_read_b128 v[152:155], v203 offset:50176
	ds_read_b128 v[156:159], v203 offset:51200
	ds_read_b128 v[170:173], v203 offset:52224
	s_add_u32 s44, s44, 0x4000
	s_addc_u32 s45, s45, 0
	s_mov_b32 m0, s78
	ds_read_b128 v[174:177], v205 offset:32768
	ds_read_b128 v[178:181], v205 offset:33792
	ds_read_b128 v[182:185], v205 offset:34816
	ds_read_b128 v[186:189], v205 offset:35840
	ds_read_b128 v[190:193], v205 offset:36864
	ds_read_b128 v[206:209], v205 offset:37888
	ds_read_b128 v[210:213], v205 offset:38912
	ds_read_b128 v[222:225], v205 offset:39936
	global_load_lds_dwordx4 v160, s[44:45]
	s_mov_b32 m0, s79
	s_nop 0
	global_load_lds_dwordx4 v162, s[44:45]
	s_waitcnt vmcnt(8)
	s_waitcnt lgkmcnt(0)
	s_barrier
	v_mfma_f32_16x16x32_bf16 v[128:131], v[132:135], v[174:177], v[128:131]
	v_mfma_f32_16x16x32_bf16 v[124:127], v[140:143], v[174:177], v[124:127]
	v_mfma_f32_16x16x32_bf16 v[112:115], v[132:135], v[182:185], v[112:115]
	v_mfma_f32_16x16x32_bf16 v[108:111], v[140:143], v[182:185], v[108:111]
	v_mfma_f32_16x16x32_bf16 v[96:99], v[132:135], v[190:193], v[96:99]
	v_mfma_f32_16x16x32_bf16 v[92:95], v[140:143], v[190:193], v[92:95]
	v_mfma_f32_16x16x32_bf16 v[88:91], v[132:135], v[210:213], v[88:91]
	v_mfma_f32_16x16x32_bf16 v[80:83], v[140:143], v[210:213], v[80:83]
	v_mfma_f32_16x16x32_bf16 v[128:131], v[136:139], v[178:181], v[128:131]
	v_mfma_f32_16x16x32_bf16 v[124:127], v[144:147], v[178:181], v[124:127]
	v_mfma_f32_16x16x32_bf16 v[112:115], v[136:139], v[186:189], v[112:115]
	v_mfma_f32_16x16x32_bf16 v[108:111], v[144:147], v[186:189], v[108:111]
	v_mfma_f32_16x16x32_bf16 v[96:99], v[136:139], v[206:209], v[96:99]
	v_mfma_f32_16x16x32_bf16 v[92:95], v[144:147], v[206:209], v[92:95]
	v_mfma_f32_16x16x32_bf16 v[88:91], v[136:139], v[222:225], v[88:91]
	v_mfma_f32_16x16x32_bf16 v[80:83], v[144:147], v[222:225], v[80:83]
	v_mfma_f32_16x16x32_bf16 v[120:123], v[148:151], v[174:177], v[120:123]
	v_mfma_f32_16x16x32_bf16 v[116:119], v[156:159], v[174:177], v[116:119]
	v_mfma_f32_16x16x32_bf16 v[104:107], v[148:151], v[182:185], v[104:107]
	v_mfma_f32_16x16x32_bf16 v[100:103], v[156:159], v[182:185], v[100:103]
	v_mfma_f32_16x16x32_bf16 v[84:87], v[148:151], v[190:193], v[84:87]
	v_mfma_f32_16x16x32_bf16 v[76:79], v[156:159], v[190:193], v[76:79]
	v_mfma_f32_16x16x32_bf16 v[72:75], v[148:151], v[210:213], v[72:75]
	v_mfma_f32_16x16x32_bf16 v[68:71], v[156:159], v[210:213], v[68:71]
	v_mfma_f32_16x16x32_bf16 v[120:123], v[152:155], v[178:181], v[120:123]
	v_mfma_f32_16x16x32_bf16 v[116:119], v[170:173], v[178:181], v[116:119]
	v_mfma_f32_16x16x32_bf16 v[104:107], v[152:155], v[186:189], v[104:107]
	v_mfma_f32_16x16x32_bf16 v[100:103], v[170:173], v[186:189], v[100:103]
	v_mfma_f32_16x16x32_bf16 v[84:87], v[152:155], v[206:209], v[84:87]
	v_mfma_f32_16x16x32_bf16 v[76:79], v[170:173], v[206:209], v[76:79]
	v_mfma_f32_16x16x32_bf16 v[72:75], v[152:155], v[222:225], v[72:75]
	v_mfma_f32_16x16x32_bf16 v[68:71], v[170:173], v[222:225], v[68:71]
	s_barrier
	s_add_u32 s44, s36, 0x40000
	s_addc_u32 s45, s37, 0
	s_add_i32 s59, s59, s75
	s_mov_b32 m0, s59
	ds_read_b128 v[174:177], v205 offset:49152
	ds_read_b128 v[178:181], v205 offset:50176
	ds_read_b128 v[182:185], v205 offset:51200
	ds_read_b128 v[186:189], v205 offset:52224
	ds_read_b128 v[190:193], v205 offset:53248
	ds_read_b128 v[206:209], v205 offset:54272
	ds_read_b128 v[210:213], v205 offset:55296
	ds_read_b128 v[222:225], v205 offset:56320
	global_load_lds_dwordx4 v2, s[44:45]
	s_add_i32 m0, s59, 0x2000
	s_add_u32 s36, s36, 0x44000
	s_addc_u32 s37, s37, 0
	global_load_lds_dwordx4 v164, s[44:45]
	s_add_i32 s44, s61, s75
	s_mov_b32 m0, s44
	s_nop 0
	global_load_lds_dwordx4 v2, s[36:37]
	s_add_i32 m0, s44, 0x2000
	s_nop 0
	global_load_lds_dwordx4 v164, s[36:37]
	s_mov_b32 m0, s82
	s_nop 0
	global_load_lds_dwordx4 v160, s[30:31]
	s_mov_b32 m0, s83
	s_nop 0
	global_load_lds_dwordx4 v162, s[30:31]
	s_waitcnt vmcnt(8)
	s_waitcnt lgkmcnt(0)
	s_barrier
	v_mfma_f32_16x16x32_bf16 v[64:67], v[132:135], v[174:177], v[64:67]
	v_mfma_f32_16x16x32_bf16 v[60:63], v[140:143], v[174:177], v[60:63]
	v_mfma_f32_16x16x32_bf16 v[48:51], v[132:135], v[182:185], v[48:51]
	v_mfma_f32_16x16x32_bf16 v[44:47], v[140:143], v[182:185], v[44:47]
	v_mfma_f32_16x16x32_bf16 v[32:35], v[132:135], v[190:193], v[32:35]
	v_mfma_f32_16x16x32_bf16 v[28:31], v[140:143], v[190:193], v[28:31]
	v_mfma_f32_16x16x32_bf16 v[16:19], v[132:135], v[210:213], v[16:19]
	v_mfma_f32_16x16x32_bf16 v[12:15], v[140:143], v[210:213], v[12:15]
	v_mfma_f32_16x16x32_bf16 v[64:67], v[136:139], v[178:181], v[64:67]
	v_mfma_f32_16x16x32_bf16 v[60:63], v[144:147], v[178:181], v[60:63]
	v_mfma_f32_16x16x32_bf16 v[48:51], v[136:139], v[186:189], v[48:51]
	v_mfma_f32_16x16x32_bf16 v[44:47], v[144:147], v[186:189], v[44:47]
	v_mfma_f32_16x16x32_bf16 v[32:35], v[136:139], v[206:209], v[32:35]
	v_mfma_f32_16x16x32_bf16 v[28:31], v[144:147], v[206:209], v[28:31]
	v_mfma_f32_16x16x32_bf16 v[16:19], v[136:139], v[222:225], v[16:19]
	v_mfma_f32_16x16x32_bf16 v[12:15], v[144:147], v[222:225], v[12:15]
	v_mfma_f32_16x16x32_bf16 v[56:59], v[148:151], v[174:177], v[56:59]
	v_mfma_f32_16x16x32_bf16 v[52:55], v[156:159], v[174:177], v[52:55]
	v_mfma_f32_16x16x32_bf16 v[40:43], v[148:151], v[182:185], v[40:43]
	v_mfma_f32_16x16x32_bf16 v[36:39], v[156:159], v[182:185], v[36:39]
	v_mfma_f32_16x16x32_bf16 v[24:27], v[148:151], v[190:193], v[24:27]
	v_mfma_f32_16x16x32_bf16 v[20:23], v[156:159], v[190:193], v[20:23]
	v_mfma_f32_16x16x32_bf16 v[8:11], v[148:151], v[210:213], v[8:11]
	v_mfma_f32_16x16x32_bf16 v[4:7], v[156:159], v[210:213], v[4:7]
	v_mfma_f32_16x16x32_bf16 v[56:59], v[152:155], v[178:181], v[56:59]
	v_mfma_f32_16x16x32_bf16 v[52:55], v[170:173], v[178:181], v[52:55]
	v_mfma_f32_16x16x32_bf16 v[40:43], v[152:155], v[186:189], v[40:43]
	v_mfma_f32_16x16x32_bf16 v[36:39], v[170:173], v[186:189], v[36:39]
	v_mfma_f32_16x16x32_bf16 v[24:27], v[152:155], v[206:209], v[24:27]
	v_mfma_f32_16x16x32_bf16 v[20:23], v[170:173], v[206:209], v[20:23]
	v_mfma_f32_16x16x32_bf16 v[8:11], v[152:155], v[222:225], v[8:11]
	v_mfma_f32_16x16x32_bf16 v[4:7], v[170:173], v[222:225], v[4:7]
	s_barrier
	s_add_i32 s58, s58, 2
	s_add_u32 s48, s48, 0x80000
	s_addc_u32 s49, s49, 0
	s_add_u32 s28, s28, 0x400000
	s_addc_u32 s29, s29, 0
	s_cmpk_gt_u32 s58, 0x55
	s_cbranch_scc0 .LBB0_433
	s_and_b64 vcc, exec, s[14:15]
	s_cbranch_vccz .LBB0_436
	s_barrier

.LBB0_576:
	s_add_u32 s27, s96, 0x1fc000
	s_addc_u32 s29, s97, 0
	s_and_b64 s[14:15], exec, s[14:15]
	s_cselect_b32 s14, s18, s27
	s_cselect_b32 s15, s7, s29
	s_add_u32 vcc_lo, s14, 0x200000
	s_addc_u32 vcc_hi, s15, 0
	s_add_i32 s27, 0, 0x10000
	s_add_i32 s29, 0, 0x14000
	ds_read_b128 v[162:165], v143
	ds_read_b128 v[166:169], v143 offset:1024
	ds_read_b128 v[172:175], v143 offset:2048
	ds_read_b128 v[176:179], v143 offset:3072
	ds_read_b128 v[180:183], v143 offset:16384
	ds_read_b128 v[184:187], v143 offset:17408
	ds_read_b128 v[188:191], v143 offset:18432
	ds_read_b128 v[192:195], v143 offset:19456
	s_add_i32 m0, s48, 0xc000
	ds_read_b128 v[200:203], v170
	ds_read_b128 v[204:207], v170 offset:1024
	ds_read_b128 v[208:211], v170 offset:2048
	ds_read_b128 v[222:225], v170 offset:3072
	ds_read_b128 v[226:229], v170 offset:4096
	ds_read_b128 v[230:233], v170 offset:5120
	ds_read_b128 v[234:237], v170 offset:6144
	ds_read_b128 v[238:241], v170 offset:7168
	global_load_lds_dwordx4 v158, s[96:97]
	s_add_i32 m0, s48, 0xe000
	s_nop 0
	global_load_lds_dwordx4 v160, s[96:97]
	s_waitcnt vmcnt(8)
	s_waitcnt lgkmcnt(0)
	s_barrier
	v_mfma_f32_16x16x32_bf16 v[128:131], v[162:165], v[200:203], v[128:131]
	v_mfma_f32_16x16x32_bf16 v[124:127], v[172:175], v[200:203], v[124:127]
	v_mfma_f32_16x16x32_bf16 v[112:115], v[162:165], v[208:211], v[112:115]
	v_mfma_f32_16x16x32_bf16 v[108:111], v[172:175], v[208:211], v[108:111]
	v_mfma_f32_16x16x32_bf16 v[96:99], v[162:165], v[226:229], v[96:99]
	v_mfma_f32_16x16x32_bf16 v[92:95], v[172:175], v[226:229], v[92:95]
	v_mfma_f32_16x16x32_bf16 v[80:83], v[162:165], v[234:237], v[80:83]
	v_mfma_f32_16x16x32_bf16 v[76:79], v[172:175], v[234:237], v[76:79]
	v_mfma_f32_16x16x32_bf16 v[128:131], v[166:169], v[204:207], v[128:131]
	v_mfma_f32_16x16x32_bf16 v[124:127], v[176:179], v[204:207], v[124:127]
	v_mfma_f32_16x16x32_bf16 v[112:115], v[166:169], v[222:225], v[112:115]
	v_mfma_f32_16x16x32_bf16 v[108:111], v[176:179], v[222:225], v[108:111]
	v_mfma_f32_16x16x32_bf16 v[96:99], v[166:169], v[230:233], v[96:99]
	v_mfma_f32_16x16x32_bf16 v[92:95], v[176:179], v[230:233], v[92:95]
	v_mfma_f32_16x16x32_bf16 v[80:83], v[166:169], v[238:241], v[80:83]
	v_mfma_f32_16x16x32_bf16 v[76:79], v[176:179], v[238:241], v[76:79]
	v_mfma_f32_16x16x32_bf16 v[120:123], v[180:183], v[200:203], v[120:123]
	v_mfma_f32_16x16x32_bf16 v[116:119], v[188:191], v[200:203], v[116:119]
	v_mfma_f32_16x16x32_bf16 v[104:107], v[180:183], v[208:211], v[104:107]
	v_mfma_f32_16x16x32_bf16 v[100:103], v[188:191], v[208:211], v[100:103]
	v_mfma_f32_16x16x32_bf16 v[88:91], v[180:183], v[226:229], v[88:91]
	v_mfma_f32_16x16x32_bf16 v[84:87], v[188:191], v[226:229], v[84:87]
	v_mfma_f32_16x16x32_bf16 v[72:75], v[180:183], v[234:237], v[72:75]
	v_mfma_f32_16x16x32_bf16 v[68:71], v[188:191], v[234:237], v[68:71]
	v_mfma_f32_16x16x32_bf16 v[120:123], v[184:187], v[204:207], v[120:123]
	v_mfma_f32_16x16x32_bf16 v[116:119], v[192:195], v[204:207], v[116:119]
	v_mfma_f32_16x16x32_bf16 v[104:107], v[184:187], v[222:225], v[104:107]
	v_mfma_f32_16x16x32_bf16 v[100:103], v[192:195], v[222:225], v[100:103]
	v_mfma_f32_16x16x32_bf16 v[88:91], v[184:187], v[230:233], v[88:91]
	v_mfma_f32_16x16x32_bf16 v[84:87], v[192:195], v[230:233], v[84:87]
	v_mfma_f32_16x16x32_bf16 v[72:75], v[184:187], v[238:241], v[72:75]
	v_mfma_f32_16x16x32_bf16 v[68:71], v[192:195], v[238:241], v[68:71]
	s_barrier
	s_add_i32 s27, s27, s90
	s_mov_b32 m0, s27
	ds_read_b128 v[200:203], v170 offset:16384
	ds_read_b128 v[204:207], v170 offset:17408
	ds_read_b128 v[208:211], v170 offset:18432
	ds_read_b128 v[222:225], v170 offset:19456
	ds_read_b128 v[226:229], v170 offset:20480
	ds_read_b128 v[230:233], v170 offset:21504
	ds_read_b128 v[234:237], v170 offset:22528
	ds_read_b128 v[238:241], v170 offset:23552
	global_load_lds_dwordx4 v134, s[72:73]
	s_add_i32 m0, s27, 0x2000
	s_add_u32 s74, s72, 0x4000
	s_addc_u32 s75, s73, 0
	s_add_i32 s27, s29, s90
	global_load_lds_dwordx4 v138, s[72:73]
	s_mov_b32 m0, s27
	s_nop 0
	global_load_lds_dwordx4 v134, s[74:75]
	s_add_i32 m0, s27, 0x2000
	s_nop 0
	global_load_lds_dwordx4 v138, s[74:75]
	s_mov_b32 m0, s48
	s_nop 0
	global_load_lds_dwordx4 v132, s[14:15]
	s_mov_b32 m0, s49
	s_nop 0
	global_load_lds_dwordx4 v136, s[14:15]
	s_waitcnt vmcnt(8)
	s_waitcnt lgkmcnt(0)
	s_nop 0
	s_barrier
	v_mfma_f32_16x16x32_bf16 v[64:67], v[162:165], v[200:203], v[64:67]
	v_mfma_f32_16x16x32_bf16 v[60:63], v[172:175], v[200:203], v[60:63]
	v_mfma_f32_16x16x32_bf16 v[48:51], v[162:165], v[208:211], v[48:51]
	v_mfma_f32_16x16x32_bf16 v[44:47], v[172:175], v[208:211], v[44:47]
	v_mfma_f32_16x16x32_bf16 v[32:35], v[162:165], v[226:229], v[32:35]
	v_mfma_f32_16x16x32_bf16 v[28:31], v[172:175], v[226:229], v[28:31]
	v_mfma_f32_16x16x32_bf16 v[16:19], v[162:165], v[234:237], v[16:19]
	v_mfma_f32_16x16x32_bf16 v[12:15], v[172:175], v[234:237], v[12:15]
	v_mfma_f32_16x16x32_bf16 v[64:67], v[166:169], v[204:207], v[64:67]
	v_mfma_f32_16x16x32_bf16 v[60:63], v[176:179], v[204:207], v[60:63]
	v_mfma_f32_16x16x32_bf16 v[48:51], v[166:169], v[222:225], v[48:51]
	v_mfma_f32_16x16x32_bf16 v[44:47], v[176:179], v[222:225], v[44:47]
	v_mfma_f32_16x16x32_bf16 v[32:35], v[166:169], v[230:233], v[32:35]
	v_mfma_f32_16x16x32_bf16 v[28:31], v[176:179], v[230:233], v[28:31]
	v_mfma_f32_16x16x32_bf16 v[16:19], v[166:169], v[238:241], v[16:19]
	v_mfma_f32_16x16x32_bf16 v[12:15], v[176:179], v[238:241], v[12:15]
	v_mfma_f32_16x16x32_bf16 v[56:59], v[180:183], v[200:203], v[56:59]
	v_mfma_f32_16x16x32_bf16 v[52:55], v[188:191], v[200:203], v[52:55]
	v_mfma_f32_16x16x32_bf16 v[40:43], v[180:183], v[208:211], v[40:43]
	v_mfma_f32_16x16x32_bf16 v[36:39], v[188:191], v[208:211], v[36:39]
	v_mfma_f32_16x16x32_bf16 v[24:27], v[180:183], v[226:229], v[24:27]
	v_mfma_f32_16x16x32_bf16 v[20:23], v[188:191], v[226:229], v[20:23]
	v_mfma_f32_16x16x32_bf16 v[8:11], v[180:183], v[234:237], v[8:11]
	v_mfma_f32_16x16x32_bf16 v[4:7], v[188:191], v[234:237], v[4:7]
	v_mfma_f32_16x16x32_bf16 v[56:59], v[184:187], v[204:207], v[56:59]
	v_mfma_f32_16x16x32_bf16 v[52:55], v[192:195], v[204:207], v[52:55]
	v_mfma_f32_16x16x32_bf16 v[40:43], v[184:187], v[222:225], v[40:43]
	v_mfma_f32_16x16x32_bf16 v[36:39], v[192:195], v[222:225], v[36:39]
	v_mfma_f32_16x16x32_bf16 v[24:27], v[184:187], v[230:233], v[24:27]
	v_mfma_f32_16x16x32_bf16 v[20:23], v[192:195], v[230:233], v[20:23]
	v_mfma_f32_16x16x32_bf16 v[8:11], v[184:187], v[238:241], v[8:11]
	v_mfma_f32_16x16x32_bf16 v[4:7], v[192:195], v[238:241], v[4:7]
	s_barrier
	s_add_i32 s27, 0, 0x18000
	s_add_i32 s29, 0, 0x1c000
	ds_read_b128 v[162:165], v143 offset:32768
	ds_read_b128 v[166:169], v143 offset:33792
	ds_read_b128 v[172:175], v143 offset:34816
	ds_read_b128 v[176:179], v143 offset:35840
	ds_read_b128 v[180:183], v143 offset:49152
	ds_read_b128 v[184:187], v143 offset:50176
	ds_read_b128 v[188:191], v143 offset:51200
	ds_read_b128 v[192:195], v143 offset:52224
	s_add_u32 s14, s14, 0x4000
	s_addc_u32 s15, s15, 0
	s_mov_b32 m0, s66
	ds_read_b128 v[200:203], v170 offset:32768
	ds_read_b128 v[204:207], v170 offset:33792
	ds_read_b128 v[208:211], v170 offset:34816
	ds_read_b128 v[222:225], v170 offset:35840
	ds_read_b128 v[226:229], v170 offset:36864
	ds_read_b128 v[230:233], v170 offset:37888
	ds_read_b128 v[234:237], v170 offset:38912
	ds_read_b128 v[238:241], v170 offset:39936
	global_load_lds_dwordx4 v132, s[14:15]
	s_mov_b32 m0, s67
	s_nop 0
	global_load_lds_dwordx4 v136, s[14:15]
	s_waitcnt vmcnt(8)
	s_waitcnt lgkmcnt(0)
	s_barrier
	v_mfma_f32_16x16x32_bf16 v[128:131], v[162:165], v[200:203], v[128:131]
	v_mfma_f32_16x16x32_bf16 v[124:127], v[172:175], v[200:203], v[124:127]
	v_mfma_f32_16x16x32_bf16 v[112:115], v[162:165], v[208:211], v[112:115]
	v_mfma_f32_16x16x32_bf16 v[108:111], v[172:175], v[208:211], v[108:111]
	v_mfma_f32_16x16x32_bf16 v[96:99], v[162:165], v[226:229], v[96:99]
	v_mfma_f32_16x16x32_bf16 v[92:95], v[172:175], v[226:229], v[92:95]
	v_mfma_f32_16x16x32_bf16 v[80:83], v[162:165], v[234:237], v[80:83]
	v_mfma_f32_16x16x32_bf16 v[76:79], v[172:175], v[234:237], v[76:79]
	v_mfma_f32_16x16x32_bf16 v[128:131], v[166:169], v[204:207], v[128:131]
	v_mfma_f32_16x16x32_bf16 v[124:127], v[176:179], v[204:207], v[124:127]
	v_mfma_f32_16x16x32_bf16 v[112:115], v[166:169], v[222:225], v[112:115]
	v_mfma_f32_16x16x32_bf16 v[108:111], v[176:179], v[222:225], v[108:111]
	v_mfma_f32_16x16x32_bf16 v[96:99], v[166:169], v[230:233], v[96:99]
	v_mfma_f32_16x16x32_bf16 v[92:95], v[176:179], v[230:233], v[92:95]
	v_mfma_f32_16x16x32_bf16 v[80:83], v[166:169], v[238:241], v[80:83]
	v_mfma_f32_16x16x32_bf16 v[76:79], v[176:179], v[238:241], v[76:79]
	v_mfma_f32_16x16x32_bf16 v[120:123], v[180:183], v[200:203], v[120:123]
	v_mfma_f32_16x16x32_bf16 v[116:119], v[188:191], v[200:203], v[116:119]
	v_mfma_f32_16x16x32_bf16 v[104:107], v[180:183], v[208:211], v[104:107]
	v_mfma_f32_16x16x32_bf16 v[100:103], v[188:191], v[208:211], v[100:103]
	v_mfma_f32_16x16x32_bf16 v[88:91], v[180:183], v[226:229], v[88:91]
	v_mfma_f32_16x16x32_bf16 v[84:87], v[188:191], v[226:229], v[84:87]
	v_mfma_f32_16x16x32_bf16 v[72:75], v[180:183], v[234:237], v[72:75]
	v_mfma_f32_16x16x32_bf16 v[68:71], v[188:191], v[234:237], v[68:71]
	v_mfma_f32_16x16x32_bf16 v[120:123], v[184:187], v[204:207], v[120:123]
	v_mfma_f32_16x16x32_bf16 v[116:119], v[192:195], v[204:207], v[116:119]
	v_mfma_f32_16x16x32_bf16 v[104:107], v[184:187], v[222:225], v[104:107]
	v_mfma_f32_16x16x32_bf16 v[100:103], v[192:195], v[222:225], v[100:103]
	v_mfma_f32_16x16x32_bf16 v[88:91], v[184:187], v[230:233], v[88:91]
	v_mfma_f32_16x16x32_bf16 v[84:87], v[192:195], v[230:233], v[84:87]
	v_mfma_f32_16x16x32_bf16 v[72:75], v[184:187], v[238:241], v[72:75]
	v_mfma_f32_16x16x32_bf16 v[68:71], v[192:195], v[238:241], v[68:71]
	s_barrier
	s_add_u32 s14, s72, 0x70000
	s_addc_u32 s15, s73, 0
	s_add_i32 s27, s27, s90
	s_mov_b32 m0, s27
	ds_read_b128 v[200:203], v170 offset:49152
	ds_read_b128 v[204:207], v170 offset:50176
	ds_read_b128 v[208:211], v170 offset:51200
	ds_read_b128 v[222:225], v170 offset:52224
	ds_read_b128 v[226:229], v170 offset:53248
	ds_read_b128 v[230:233], v170 offset:54272
	ds_read_b128 v[234:237], v170 offset:55296
	ds_read_b128 v[238:241], v170 offset:56320
	global_load_lds_dwordx4 v134, s[14:15]
	s_add_i32 m0, s27, 0x2000
	s_nop 0
	global_load_lds_dwordx4 v138, s[14:15]
	s_add_u32 s14, s72, 0x74000
	s_addc_u32 s15, s73, 0
	s_add_i32 s27, s29, s90
	s_mov_b32 m0, s27
	s_nop 0
	global_load_lds_dwordx4 v134, s[14:15]
	s_add_i32 m0, s27, 0x2000
	s_nop 0
	global_load_lds_dwordx4 v138, s[14:15]
	s_mov_b32 m0, s59
	s_nop 0
	global_load_lds_dwordx4 v132, vcc
	s_mov_b32 m0, s70
	s_nop 0
	global_load_lds_dwordx4 v136, vcc
	s_waitcnt vmcnt(8)
	s_waitcnt lgkmcnt(0)
	s_nop 0
	s_barrier
	v_mfma_f32_16x16x32_bf16 v[64:67], v[162:165], v[200:203], v[64:67]
	v_mfma_f32_16x16x32_bf16 v[60:63], v[172:175], v[200:203], v[60:63]
	v_mfma_f32_16x16x32_bf16 v[48:51], v[162:165], v[208:211], v[48:51]
	v_mfma_f32_16x16x32_bf16 v[44:47], v[172:175], v[208:211], v[44:47]
	v_mfma_f32_16x16x32_bf16 v[32:35], v[162:165], v[226:229], v[32:35]
	v_mfma_f32_16x16x32_bf16 v[28:31], v[172:175], v[226:229], v[28:31]
	v_mfma_f32_16x16x32_bf16 v[16:19], v[162:165], v[234:237], v[16:19]
	v_mfma_f32_16x16x32_bf16 v[12:15], v[172:175], v[234:237], v[12:15]
	v_mfma_f32_16x16x32_bf16 v[64:67], v[166:169], v[204:207], v[64:67]
	v_mfma_f32_16x16x32_bf16 v[60:63], v[176:179], v[204:207], v[60:63]
	v_mfma_f32_16x16x32_bf16 v[48:51], v[166:169], v[222:225], v[48:51]
	v_mfma_f32_16x16x32_bf16 v[44:47], v[176:179], v[222:225], v[44:47]
	v_mfma_f32_16x16x32_bf16 v[32:35], v[166:169], v[230:233], v[32:35]
	v_mfma_f32_16x16x32_bf16 v[28:31], v[176:179], v[230:233], v[28:31]
	v_mfma_f32_16x16x32_bf16 v[16:19], v[166:169], v[238:241], v[16:19]
	v_mfma_f32_16x16x32_bf16 v[12:15], v[176:179], v[238:241], v[12:15]
	v_mfma_f32_16x16x32_bf16 v[56:59], v[180:183], v[200:203], v[56:59]
	v_mfma_f32_16x16x32_bf16 v[52:55], v[188:191], v[200:203], v[52:55]
	v_mfma_f32_16x16x32_bf16 v[40:43], v[180:183], v[208:211], v[40:43]
	v_mfma_f32_16x16x32_bf16 v[36:39], v[188:191], v[208:211], v[36:39]
	v_mfma_f32_16x16x32_bf16 v[24:27], v[180:183], v[226:229], v[24:27]
	v_mfma_f32_16x16x32_bf16 v[20:23], v[188:191], v[226:229], v[20:23]
	v_mfma_f32_16x16x32_bf16 v[8:11], v[180:183], v[234:237], v[8:11]
	v_mfma_f32_16x16x32_bf16 v[4:7], v[188:191], v[234:237], v[4:7]
	v_mfma_f32_16x16x32_bf16 v[56:59], v[184:187], v[204:207], v[56:59]
	v_mfma_f32_16x16x32_bf16 v[52:55], v[192:195], v[204:207], v[52:55]
	v_mfma_f32_16x16x32_bf16 v[40:43], v[184:187], v[222:225], v[40:43]
	v_mfma_f32_16x16x32_bf16 v[36:39], v[192:195], v[222:225], v[36:39]
	v_mfma_f32_16x16x32_bf16 v[24:27], v[184:187], v[230:233], v[24:27]
	v_mfma_f32_16x16x32_bf16 v[20:23], v[192:195], v[230:233], v[20:23]
	v_mfma_f32_16x16x32_bf16 v[8:11], v[184:187], v[238:241], v[8:11]
	v_mfma_f32_16x16x32_bf16 v[4:7], v[192:195], v[238:241], v[4:7]
	s_barrier
	s_add_i32 s19, s19, 2
	s_add_u32 s94, s94, 0xe0000
	s_addc_u32 s95, s95, 0
	s_add_u32 s96, s96, 0x400000
	s_addc_u32 s97, s97, 0
	s_cmp_gt_u32 s19, 29
	s_cbranch_scc1 .LBB0_579

.LBB0_881:
	s_add_u32 s29, s46, 0x1fc000
	s_addc_u32 s48, s47, 0
	s_and_b64 s[34:35], exec, s[72:73]
	s_cselect_b32 s74, s27, s29
	s_cselect_b32 s75, s21, s48
	s_add_u32 s72, s74, 0x200000
	s_addc_u32 s73, s75, 0
	s_add_i32 s29, 0, 0x10000
	s_add_i32 s48, 0, 0x14000
	ds_read_b128 v[100:103], v222
	ds_read_b128 v[104:107], v222 offset:1024
	ds_read_b128 v[108:111], v222 offset:2048
	ds_read_b128 v[112:115], v222 offset:3072
	ds_read_b128 v[116:119], v222 offset:16384
	ds_read_b128 v[124:127], v222 offset:17408
	ds_read_b128 v[132:135], v222 offset:18432
	ds_read_b128 v[136:139], v222 offset:19456
	s_add_i32 m0, s82, 0xc000
	ds_read_b128 v[140:143], v227
	ds_read_b128 v[144:147], v227 offset:1024
	ds_read_b128 v[156:159], v227 offset:2048
	ds_read_b128 v[160:163], v227 offset:3072
	ds_read_b128 v[164:167], v227 offset:4096
	ds_read_b128 v[172:175], v227 offset:5120
	ds_read_b128 v[180:183], v227 offset:6144
	ds_read_b128 v[184:187], v227 offset:7168
	global_load_lds_dwordx4 v208, s[46:47]
	s_add_i32 m0, s82, 0xe000
	s_nop 0
	global_load_lds_dwordx4 v210, s[46:47]
	s_waitcnt vmcnt(8)
	s_waitcnt lgkmcnt(0)
	s_barrier
	v_mfma_f32_16x16x32_bf16 v[192:195], v[100:103], v[140:143], v[192:195]
	v_mfma_f32_16x16x32_bf16 v[188:191], v[108:111], v[140:143], v[188:191]
	v_mfma_f32_16x16x32_bf16 v[176:179], v[100:103], v[156:159], v[176:179]
	v_mfma_f32_16x16x32_bf16 v[168:171], v[108:111], v[156:159], v[168:171]
	v_mfma_f32_16x16x32_bf16 v[152:155], v[100:103], v[164:167], v[152:155]
	v_mfma_f32_16x16x32_bf16 v[148:151], v[108:111], v[164:167], v[148:151]
	v_mfma_f32_16x16x32_bf16 v[128:131], v[100:103], v[180:183], v[128:131]
	v_mfma_f32_16x16x32_bf16 v[120:123], v[108:111], v[180:183], v[120:123]
	v_mfma_f32_16x16x32_bf16 v[192:195], v[104:107], v[144:147], v[192:195]
	v_mfma_f32_16x16x32_bf16 v[188:191], v[112:115], v[144:147], v[188:191]
	v_mfma_f32_16x16x32_bf16 v[176:179], v[104:107], v[160:163], v[176:179]
	v_mfma_f32_16x16x32_bf16 v[168:171], v[112:115], v[160:163], v[168:171]
	v_mfma_f32_16x16x32_bf16 v[152:155], v[104:107], v[172:175], v[152:155]
	v_mfma_f32_16x16x32_bf16 v[148:151], v[112:115], v[172:175], v[148:151]
	v_mfma_f32_16x16x32_bf16 v[128:131], v[104:107], v[184:187], v[128:131]
	v_mfma_f32_16x16x32_bf16 v[120:123], v[112:115], v[184:187], v[120:123]
	v_mfma_f32_16x16x32_bf16 v[64:67], v[116:119], v[140:143], v[64:67]
	v_mfma_f32_16x16x32_bf16 v[60:63], v[132:135], v[140:143], v[60:63]
	v_mfma_f32_16x16x32_bf16 v[56:59], v[116:119], v[156:159], v[56:59]
	v_mfma_f32_16x16x32_bf16 v[52:55], v[132:135], v[156:159], v[52:55]
	v_mfma_f32_16x16x32_bf16 v[48:51], v[116:119], v[164:167], v[48:51]
	v_mfma_f32_16x16x32_bf16 v[44:47], v[132:135], v[164:167], v[44:47]
	v_mfma_f32_16x16x32_bf16 v[40:43], v[116:119], v[180:183], v[40:43]
	v_mfma_f32_16x16x32_bf16 v[36:39], v[132:135], v[180:183], v[36:39]
	v_mfma_f32_16x16x32_bf16 v[64:67], v[124:127], v[144:147], v[64:67]
	v_mfma_f32_16x16x32_bf16 v[60:63], v[136:139], v[144:147], v[60:63]
	v_mfma_f32_16x16x32_bf16 v[56:59], v[124:127], v[160:163], v[56:59]
	v_mfma_f32_16x16x32_bf16 v[52:55], v[136:139], v[160:163], v[52:55]
	v_mfma_f32_16x16x32_bf16 v[48:51], v[124:127], v[172:175], v[48:51]
	v_mfma_f32_16x16x32_bf16 v[44:47], v[136:139], v[172:175], v[44:47]
	v_mfma_f32_16x16x32_bf16 v[40:43], v[124:127], v[184:187], v[40:43]
	v_mfma_f32_16x16x32_bf16 v[36:39], v[136:139], v[184:187], v[36:39]
	s_barrier
	s_add_i32 s29, s29, s79
	s_mov_b32 m0, s29
	ds_read_b128 v[140:143], v227 offset:16384
	ds_read_b128 v[144:147], v227 offset:17408
	ds_read_b128 v[156:159], v227 offset:18432
	ds_read_b128 v[160:163], v227 offset:19456
	ds_read_b128 v[164:167], v227 offset:20480
	ds_read_b128 v[172:175], v227 offset:21504
	ds_read_b128 v[180:183], v227 offset:22528
	ds_read_b128 v[184:187], v227 offset:23552
	global_load_lds_dwordx4 v202, s[36:37]
	s_add_i32 m0, s29, 0x2000
	s_add_u32 s34, s36, 0x4000
	s_addc_u32 s35, s37, 0
	s_add_i32 s29, s48, s79
	global_load_lds_dwordx4 v206, s[36:37]
	s_mov_b32 m0, s29
	s_nop 0
	global_load_lds_dwordx4 v202, s[34:35]
	s_add_i32 m0, s29, 0x2000
	s_nop 0
	global_load_lds_dwordx4 v206, s[34:35]
	s_mov_b32 m0, s82
	s_nop 0
	global_load_lds_dwordx4 v200, s[74:75]
	s_mov_b32 m0, s83
	s_nop 0
	global_load_lds_dwordx4 v204, s[74:75]
	s_waitcnt vmcnt(8)
	s_waitcnt lgkmcnt(0)
	s_nop 0
	s_barrier
	v_mfma_f32_16x16x32_bf16 v[96:99], v[100:103], v[140:143], v[96:99]
	v_mfma_f32_16x16x32_bf16 v[92:95], v[108:111], v[140:143], v[92:95]
	v_mfma_f32_16x16x32_bf16 v[88:91], v[100:103], v[156:159], v[88:91]
	v_mfma_f32_16x16x32_bf16 v[84:87], v[108:111], v[156:159], v[84:87]
	v_mfma_f32_16x16x32_bf16 v[80:83], v[100:103], v[164:167], v[80:83]
	v_mfma_f32_16x16x32_bf16 v[76:79], v[108:111], v[164:167], v[76:79]
	v_mfma_f32_16x16x32_bf16 v[72:75], v[100:103], v[180:183], v[72:75]
	v_mfma_f32_16x16x32_bf16 v[68:71], v[108:111], v[180:183], v[68:71]
	v_mfma_f32_16x16x32_bf16 v[96:99], v[104:107], v[144:147], v[96:99]
	v_mfma_f32_16x16x32_bf16 v[92:95], v[112:115], v[144:147], v[92:95]
	v_mfma_f32_16x16x32_bf16 v[88:91], v[104:107], v[160:163], v[88:91]
	v_mfma_f32_16x16x32_bf16 v[84:87], v[112:115], v[160:163], v[84:87]
	v_mfma_f32_16x16x32_bf16 v[80:83], v[104:107], v[172:175], v[80:83]
	v_mfma_f32_16x16x32_bf16 v[76:79], v[112:115], v[172:175], v[76:79]
	v_mfma_f32_16x16x32_bf16 v[72:75], v[104:107], v[184:187], v[72:75]
	v_mfma_f32_16x16x32_bf16 v[68:71], v[112:115], v[184:187], v[68:71]
	v_mfma_f32_16x16x32_bf16 v[32:35], v[116:119], v[140:143], v[32:35]
	v_mfma_f32_16x16x32_bf16 v[28:31], v[132:135], v[140:143], v[28:31]
	v_mfma_f32_16x16x32_bf16 v[24:27], v[116:119], v[156:159], v[24:27]
	v_mfma_f32_16x16x32_bf16 v[20:23], v[132:135], v[156:159], v[20:23]
	v_mfma_f32_16x16x32_bf16 v[16:19], v[116:119], v[164:167], v[16:19]
	v_mfma_f32_16x16x32_bf16 v[12:15], v[132:135], v[164:167], v[12:15]
	v_mfma_f32_16x16x32_bf16 v[8:11], v[116:119], v[180:183], v[8:11]
	v_mfma_f32_16x16x32_bf16 v[4:7], v[132:135], v[180:183], v[4:7]
	v_mfma_f32_16x16x32_bf16 v[32:35], v[124:127], v[144:147], v[32:35]
	v_mfma_f32_16x16x32_bf16 v[28:31], v[136:139], v[144:147], v[28:31]
	v_mfma_f32_16x16x32_bf16 v[24:27], v[124:127], v[160:163], v[24:27]
	v_mfma_f32_16x16x32_bf16 v[20:23], v[136:139], v[160:163], v[20:23]
	v_mfma_f32_16x16x32_bf16 v[16:19], v[124:127], v[172:175], v[16:19]
	v_mfma_f32_16x16x32_bf16 v[12:15], v[136:139], v[172:175], v[12:15]
	v_mfma_f32_16x16x32_bf16 v[8:11], v[124:127], v[184:187], v[8:11]
	v_mfma_f32_16x16x32_bf16 v[4:7], v[136:139], v[184:187], v[4:7]
	s_barrier
	s_add_i32 s29, 0, 0x18000
	s_add_i32 s48, 0, 0x1c000
	ds_read_b128 v[100:103], v222 offset:32768
	ds_read_b128 v[104:107], v222 offset:33792
	ds_read_b128 v[108:111], v222 offset:34816
	ds_read_b128 v[112:115], v222 offset:35840
	ds_read_b128 v[116:119], v222 offset:49152
	ds_read_b128 v[124:127], v222 offset:50176
	ds_read_b128 v[132:135], v222 offset:51200
	ds_read_b128 v[136:139], v222 offset:52224
	s_add_u32 s34, s74, 0x4000
	s_addc_u32 s35, s75, 0
	s_mov_b32 m0, s86
	ds_read_b128 v[140:143], v227 offset:32768
	ds_read_b128 v[144:147], v227 offset:33792
	ds_read_b128 v[156:159], v227 offset:34816
	ds_read_b128 v[160:163], v227 offset:35840
	ds_read_b128 v[164:167], v227 offset:36864
	ds_read_b128 v[172:175], v227 offset:37888
	ds_read_b128 v[180:183], v227 offset:38912
	ds_read_b128 v[184:187], v227 offset:39936
	global_load_lds_dwordx4 v200, s[34:35]
	s_mov_b32 m0, s87
	s_nop 0
	global_load_lds_dwordx4 v204, s[34:35]
	s_waitcnt vmcnt(8)
	s_waitcnt lgkmcnt(0)
	s_barrier
	v_mfma_f32_16x16x32_bf16 v[192:195], v[100:103], v[140:143], v[192:195]
	v_mfma_f32_16x16x32_bf16 v[188:191], v[108:111], v[140:143], v[188:191]
	v_mfma_f32_16x16x32_bf16 v[176:179], v[100:103], v[156:159], v[176:179]
	v_mfma_f32_16x16x32_bf16 v[168:171], v[108:111], v[156:159], v[168:171]
	v_mfma_f32_16x16x32_bf16 v[152:155], v[100:103], v[164:167], v[152:155]
	v_mfma_f32_16x16x32_bf16 v[148:151], v[108:111], v[164:167], v[148:151]
	v_mfma_f32_16x16x32_bf16 v[128:131], v[100:103], v[180:183], v[128:131]
	v_mfma_f32_16x16x32_bf16 v[120:123], v[108:111], v[180:183], v[120:123]
	v_mfma_f32_16x16x32_bf16 v[192:195], v[104:107], v[144:147], v[192:195]
	v_mfma_f32_16x16x32_bf16 v[188:191], v[112:115], v[144:147], v[188:191]
	v_mfma_f32_16x16x32_bf16 v[176:179], v[104:107], v[160:163], v[176:179]
	v_mfma_f32_16x16x32_bf16 v[168:171], v[112:115], v[160:163], v[168:171]
	v_mfma_f32_16x16x32_bf16 v[152:155], v[104:107], v[172:175], v[152:155]
	v_mfma_f32_16x16x32_bf16 v[148:151], v[112:115], v[172:175], v[148:151]
	v_mfma_f32_16x16x32_bf16 v[128:131], v[104:107], v[184:187], v[128:131]
	v_mfma_f32_16x16x32_bf16 v[120:123], v[112:115], v[184:187], v[120:123]
	v_mfma_f32_16x16x32_bf16 v[64:67], v[116:119], v[140:143], v[64:67]
	v_mfma_f32_16x16x32_bf16 v[60:63], v[132:135], v[140:143], v[60:63]
	v_mfma_f32_16x16x32_bf16 v[56:59], v[116:119], v[156:159], v[56:59]
	v_mfma_f32_16x16x32_bf16 v[52:55], v[132:135], v[156:159], v[52:55]
	v_mfma_f32_16x16x32_bf16 v[48:51], v[116:119], v[164:167], v[48:51]
	v_mfma_f32_16x16x32_bf16 v[44:47], v[132:135], v[164:167], v[44:47]
	v_mfma_f32_16x16x32_bf16 v[40:43], v[116:119], v[180:183], v[40:43]
	v_mfma_f32_16x16x32_bf16 v[36:39], v[132:135], v[180:183], v[36:39]
	v_mfma_f32_16x16x32_bf16 v[64:67], v[124:127], v[144:147], v[64:67]
	v_mfma_f32_16x16x32_bf16 v[60:63], v[136:139], v[144:147], v[60:63]
	v_mfma_f32_16x16x32_bf16 v[56:59], v[124:127], v[160:163], v[56:59]
	v_mfma_f32_16x16x32_bf16 v[52:55], v[136:139], v[160:163], v[52:55]
	v_mfma_f32_16x16x32_bf16 v[48:51], v[124:127], v[172:175], v[48:51]
	v_mfma_f32_16x16x32_bf16 v[44:47], v[136:139], v[172:175], v[44:47]
	v_mfma_f32_16x16x32_bf16 v[40:43], v[124:127], v[184:187], v[40:43]
	v_mfma_f32_16x16x32_bf16 v[36:39], v[136:139], v[184:187], v[36:39]
	s_barrier
	s_add_u32 s34, s36, 0x30000
	s_addc_u32 s35, s37, 0
	s_add_i32 s29, s29, s79
	s_mov_b32 m0, s29
	ds_read_b128 v[140:143], v227 offset:49152
	ds_read_b128 v[144:147], v227 offset:50176
	ds_read_b128 v[156:159], v227 offset:51200
	ds_read_b128 v[160:163], v227 offset:52224
	ds_read_b128 v[164:167], v227 offset:53248
	ds_read_b128 v[172:175], v227 offset:54272
	ds_read_b128 v[180:183], v227 offset:55296
	ds_read_b128 v[184:187], v227 offset:56320
	global_load_lds_dwordx4 v202, s[34:35]
	s_add_i32 m0, s29, 0x2000
	s_nop 0
	global_load_lds_dwordx4 v206, s[34:35]
	s_add_u32 s34, s36, 0x34000
	s_addc_u32 s35, s37, 0
	s_add_i32 s29, s48, s79
	s_mov_b32 m0, s29
	s_nop 0
	global_load_lds_dwordx4 v202, s[34:35]
	s_add_i32 m0, s29, 0x2000
	s_nop 0
	global_load_lds_dwordx4 v206, s[34:35]
	s_mov_b32 m0, s94
	s_nop 0
	global_load_lds_dwordx4 v200, s[72:73]
	s_mov_b32 m0, s95
	s_nop 0
	global_load_lds_dwordx4 v204, s[72:73]
	s_waitcnt vmcnt(8)
	s_waitcnt lgkmcnt(0)
	s_nop 0
	s_barrier
	v_mfma_f32_16x16x32_bf16 v[96:99], v[100:103], v[140:143], v[96:99]
	v_mfma_f32_16x16x32_bf16 v[92:95], v[108:111], v[140:143], v[92:95]
	v_mfma_f32_16x16x32_bf16 v[88:91], v[100:103], v[156:159], v[88:91]
	v_mfma_f32_16x16x32_bf16 v[84:87], v[108:111], v[156:159], v[84:87]
	v_mfma_f32_16x16x32_bf16 v[80:83], v[100:103], v[164:167], v[80:83]
	v_mfma_f32_16x16x32_bf16 v[76:79], v[108:111], v[164:167], v[76:79]
	v_mfma_f32_16x16x32_bf16 v[72:75], v[100:103], v[180:183], v[72:75]
	v_mfma_f32_16x16x32_bf16 v[68:71], v[108:111], v[180:183], v[68:71]
	v_mfma_f32_16x16x32_bf16 v[96:99], v[104:107], v[144:147], v[96:99]
	v_mfma_f32_16x16x32_bf16 v[92:95], v[112:115], v[144:147], v[92:95]
	v_mfma_f32_16x16x32_bf16 v[88:91], v[104:107], v[160:163], v[88:91]
	v_mfma_f32_16x16x32_bf16 v[84:87], v[112:115], v[160:163], v[84:87]
	v_mfma_f32_16x16x32_bf16 v[80:83], v[104:107], v[172:175], v[80:83]
	v_mfma_f32_16x16x32_bf16 v[76:79], v[112:115], v[172:175], v[76:79]
	v_mfma_f32_16x16x32_bf16 v[72:75], v[104:107], v[184:187], v[72:75]
	v_mfma_f32_16x16x32_bf16 v[68:71], v[112:115], v[184:187], v[68:71]
	v_mfma_f32_16x16x32_bf16 v[32:35], v[116:119], v[140:143], v[32:35]
	v_mfma_f32_16x16x32_bf16 v[28:31], v[132:135], v[140:143], v[28:31]
	v_mfma_f32_16x16x32_bf16 v[24:27], v[116:119], v[156:159], v[24:27]
	v_mfma_f32_16x16x32_bf16 v[20:23], v[132:135], v[156:159], v[20:23]
	v_mfma_f32_16x16x32_bf16 v[16:19], v[116:119], v[164:167], v[16:19]
	v_mfma_f32_16x16x32_bf16 v[12:15], v[132:135], v[164:167], v[12:15]
	v_mfma_f32_16x16x32_bf16 v[8:11], v[116:119], v[180:183], v[8:11]
	v_mfma_f32_16x16x32_bf16 v[4:7], v[132:135], v[180:183], v[4:7]
	v_mfma_f32_16x16x32_bf16 v[32:35], v[124:127], v[144:147], v[32:35]
	v_mfma_f32_16x16x32_bf16 v[28:31], v[136:139], v[144:147], v[28:31]
	v_mfma_f32_16x16x32_bf16 v[24:27], v[124:127], v[160:163], v[24:27]
	v_mfma_f32_16x16x32_bf16 v[20:23], v[136:139], v[160:163], v[20:23]
	v_mfma_f32_16x16x32_bf16 v[16:19], v[124:127], v[172:175], v[16:19]
	v_mfma_f32_16x16x32_bf16 v[12:15], v[136:139], v[172:175], v[12:15]
	v_mfma_f32_16x16x32_bf16 v[8:11], v[124:127], v[184:187], v[8:11]
	v_mfma_f32_16x16x32_bf16 v[4:7], v[136:139], v[184:187], v[4:7]
	s_barrier
	s_add_i32 s19, s19, 2
	s_add_u32 s44, s44, 0x60000
	s_addc_u32 s45, s45, 0
	s_add_u32 s46, s46, 0x400000
	s_addc_u32 s47, s47, 0
	s_cmp_gt_u32 s19, 5
	s_cbranch_scc1 .LBB0_884

.LBB0_936:
	s_or_b32 s83, s82, 1
	s_mul_hi_u32 s86, s83, 0x280000
	s_mul_i32 s83, s83, 0x280000
	s_add_u32 s83, s46, s83
	s_addc_u32 s86, s47, s86
	s_add_u32 s76, s44, s76
	s_addc_u32 s77, s45, s77
	s_and_b64 s[74:75], exec, s[74:75]
	s_cselect_b32 s97, s23, s77
	s_cselect_b32 s96, s25, s76
	s_add_u32 s94, s36, 0x280000
	s_addc_u32 s95, s37, 0
	s_add_i32 s76, 0, 0x10000
	s_add_i32 s77, 0, 0x14000
	ds_read_b128 v[142:145], v140
	ds_read_b128 v[146:149], v140 offset:1024
	ds_read_b128 v[150:153], v140 offset:2048
	ds_read_b128 v[154:157], v140 offset:3072
	ds_read_b128 v[158:161], v140 offset:16384
	ds_read_b128 v[162:165], v140 offset:17408
	ds_read_b128 v[166:169], v140 offset:18432
	ds_read_b128 v[170:173], v140 offset:19456
	s_add_u32 s74, s83, 0x4000
	s_addc_u32 s75, s86, 0
	s_add_i32 m0, s31, 0xc000
	ds_read_b128 v[174:177], v141
	ds_read_b128 v[178:181], v141 offset:1024
	ds_read_b128 v[182:185], v141 offset:2048
	ds_read_b128 v[186:189], v141 offset:3072
	ds_read_b128 v[190:193], v141 offset:4096
	ds_read_b128 v[200:203], v141 offset:5120
	ds_read_b128 v[204:207], v141 offset:6144
	ds_read_b128 v[208:211], v141 offset:7168
	global_load_lds_dwordx4 v136, s[74:75]
	s_add_i32 m0, s31, 0xe000
	s_nop 0
	global_load_lds_dwordx4 v134, s[74:75]
	s_waitcnt vmcnt(8)
	s_waitcnt lgkmcnt(0)
	s_barrier
	v_mfma_f32_16x16x32_bf16 v[128:131], v[142:145], v[174:177], v[128:131]
	v_mfma_f32_16x16x32_bf16 v[124:127], v[150:153], v[174:177], v[124:127]
	v_mfma_f32_16x16x32_bf16 v[120:123], v[142:145], v[182:185], v[120:123]
	v_mfma_f32_16x16x32_bf16 v[112:115], v[150:153], v[182:185], v[112:115]
	v_mfma_f32_16x16x32_bf16 v[104:107], v[142:145], v[190:193], v[104:107]
	v_mfma_f32_16x16x32_bf16 v[96:99], v[150:153], v[190:193], v[96:99]
	v_mfma_f32_16x16x32_bf16 v[88:91], v[142:145], v[204:207], v[88:91]
	v_mfma_f32_16x16x32_bf16 v[80:83], v[150:153], v[204:207], v[80:83]
	v_mfma_f32_16x16x32_bf16 v[128:131], v[146:149], v[178:181], v[128:131]
	v_mfma_f32_16x16x32_bf16 v[124:127], v[154:157], v[178:181], v[124:127]
	v_mfma_f32_16x16x32_bf16 v[120:123], v[146:149], v[186:189], v[120:123]
	v_mfma_f32_16x16x32_bf16 v[112:115], v[154:157], v[186:189], v[112:115]
	v_mfma_f32_16x16x32_bf16 v[104:107], v[146:149], v[200:203], v[104:107]
	v_mfma_f32_16x16x32_bf16 v[96:99], v[154:157], v[200:203], v[96:99]
	v_mfma_f32_16x16x32_bf16 v[88:91], v[146:149], v[208:211], v[88:91]
	v_mfma_f32_16x16x32_bf16 v[80:83], v[154:157], v[208:211], v[80:83]
	v_mfma_f32_16x16x32_bf16 v[116:119], v[158:161], v[174:177], v[116:119]
	v_mfma_f32_16x16x32_bf16 v[108:111], v[166:169], v[174:177], v[108:111]
	v_mfma_f32_16x16x32_bf16 v[100:103], v[158:161], v[182:185], v[100:103]
	v_mfma_f32_16x16x32_bf16 v[92:95], v[166:169], v[182:185], v[92:95]
	v_mfma_f32_16x16x32_bf16 v[84:87], v[158:161], v[190:193], v[84:87]
	v_mfma_f32_16x16x32_bf16 v[76:79], v[166:169], v[190:193], v[76:79]
	v_mfma_f32_16x16x32_bf16 v[72:75], v[158:161], v[204:207], v[72:75]
	v_mfma_f32_16x16x32_bf16 v[68:71], v[166:169], v[204:207], v[68:71]
	v_mfma_f32_16x16x32_bf16 v[116:119], v[162:165], v[178:181], v[116:119]
	v_mfma_f32_16x16x32_bf16 v[108:111], v[170:173], v[178:181], v[108:111]
	v_mfma_f32_16x16x32_bf16 v[100:103], v[162:165], v[186:189], v[100:103]
	v_mfma_f32_16x16x32_bf16 v[92:95], v[170:173], v[186:189], v[92:95]
	v_mfma_f32_16x16x32_bf16 v[84:87], v[162:165], v[200:203], v[84:87]
	v_mfma_f32_16x16x32_bf16 v[76:79], v[170:173], v[200:203], v[76:79]
	v_mfma_f32_16x16x32_bf16 v[72:75], v[162:165], v[208:211], v[72:75]
	v_mfma_f32_16x16x32_bf16 v[68:71], v[170:173], v[208:211], v[68:71]
	s_barrier
	s_add_i32 s74, s76, s58
	s_mov_b32 m0, s74
	ds_read_b128 v[174:177], v141 offset:16384
	ds_read_b128 v[178:181], v141 offset:17408
	ds_read_b128 v[182:185], v141 offset:18432
	ds_read_b128 v[186:189], v141 offset:19456
	ds_read_b128 v[190:193], v141 offset:20480
	ds_read_b128 v[200:203], v141 offset:21504
	ds_read_b128 v[204:207], v141 offset:22528
	ds_read_b128 v[208:211], v141 offset:23552
	global_load_lds_dwordx4 v2, s[96:97]
	s_add_i32 m0, s74, 0x2000
	s_add_u32 s74, s96, 0x4000
	s_addc_u32 s75, s97, 0
	s_add_i32 s76, s77, s58
	global_load_lds_dwordx4 v132, s[96:97]
	s_mov_b32 m0, s76
	s_nop 0
	global_load_lds_dwordx4 v2, s[74:75]
	s_add_i32 m0, s76, 0x2000
	s_nop 0
	global_load_lds_dwordx4 v132, s[74:75]
	s_mov_b32 m0, s31
	s_nop 0
	global_load_lds_dwordx4 v136, s[36:37]
	s_mov_b32 m0, s61
	s_nop 0
	global_load_lds_dwordx4 v134, s[36:37]
	s_waitcnt vmcnt(8)
	s_waitcnt lgkmcnt(0)
	s_nop 0
	s_barrier
	v_mfma_f32_16x16x32_bf16 v[64:67], v[142:145], v[174:177], v[64:67]
	v_mfma_f32_16x16x32_bf16 v[60:63], v[150:153], v[174:177], v[60:63]
	v_mfma_f32_16x16x32_bf16 v[56:59], v[142:145], v[182:185], v[56:59]
	v_mfma_f32_16x16x32_bf16 v[48:51], v[150:153], v[182:185], v[48:51]
	v_mfma_f32_16x16x32_bf16 v[40:43], v[142:145], v[190:193], v[40:43]
	v_mfma_f32_16x16x32_bf16 v[32:35], v[150:153], v[190:193], v[32:35]
	v_mfma_f32_16x16x32_bf16 v[24:27], v[142:145], v[204:207], v[24:27]
	v_mfma_f32_16x16x32_bf16 v[16:19], v[150:153], v[204:207], v[16:19]
	v_mfma_f32_16x16x32_bf16 v[64:67], v[146:149], v[178:181], v[64:67]
	v_mfma_f32_16x16x32_bf16 v[60:63], v[154:157], v[178:181], v[60:63]
	v_mfma_f32_16x16x32_bf16 v[56:59], v[146:149], v[186:189], v[56:59]
	v_mfma_f32_16x16x32_bf16 v[48:51], v[154:157], v[186:189], v[48:51]
	v_mfma_f32_16x16x32_bf16 v[40:43], v[146:149], v[200:203], v[40:43]
	v_mfma_f32_16x16x32_bf16 v[32:35], v[154:157], v[200:203], v[32:35]
	v_mfma_f32_16x16x32_bf16 v[24:27], v[146:149], v[208:211], v[24:27]
	v_mfma_f32_16x16x32_bf16 v[16:19], v[154:157], v[208:211], v[16:19]
	v_mfma_f32_16x16x32_bf16 v[52:55], v[158:161], v[174:177], v[52:55]
	v_mfma_f32_16x16x32_bf16 v[44:47], v[166:169], v[174:177], v[44:47]
	v_mfma_f32_16x16x32_bf16 v[36:39], v[158:161], v[182:185], v[36:39]
	v_mfma_f32_16x16x32_bf16 v[28:31], v[166:169], v[182:185], v[28:31]
	v_mfma_f32_16x16x32_bf16 v[20:23], v[158:161], v[190:193], v[20:23]
	v_mfma_f32_16x16x32_bf16 v[12:15], v[166:169], v[190:193], v[12:15]
	v_mfma_f32_16x16x32_bf16 v[8:11], v[158:161], v[204:207], v[8:11]
	v_mfma_f32_16x16x32_bf16 v[4:7], v[166:169], v[204:207], v[4:7]
	v_mfma_f32_16x16x32_bf16 v[52:55], v[162:165], v[178:181], v[52:55]
	v_mfma_f32_16x16x32_bf16 v[44:47], v[170:173], v[178:181], v[44:47]
	v_mfma_f32_16x16x32_bf16 v[36:39], v[162:165], v[186:189], v[36:39]
	v_mfma_f32_16x16x32_bf16 v[28:31], v[170:173], v[186:189], v[28:31]
	v_mfma_f32_16x16x32_bf16 v[20:23], v[162:165], v[200:203], v[20:23]
	v_mfma_f32_16x16x32_bf16 v[12:15], v[170:173], v[200:203], v[12:15]
	v_mfma_f32_16x16x32_bf16 v[8:11], v[162:165], v[208:211], v[8:11]
	v_mfma_f32_16x16x32_bf16 v[4:7], v[170:173], v[208:211], v[4:7]
	s_barrier
	s_add_i32 s74, 0, 0x18000
	s_add_i32 s75, 0, 0x1c000
	ds_read_b128 v[142:145], v140 offset:32768
	ds_read_b128 v[146:149], v140 offset:33792
	ds_read_b128 v[150:153], v140 offset:34816
	ds_read_b128 v[154:157], v140 offset:35840
	ds_read_b128 v[158:161], v140 offset:49152
	ds_read_b128 v[162:165], v140 offset:50176
	ds_read_b128 v[166:169], v140 offset:51200
	ds_read_b128 v[170:173], v140 offset:52224
	s_add_u32 s36, s36, 0x4000
	s_addc_u32 s37, s37, 0
	s_mov_b32 m0, s66
	ds_read_b128 v[174:177], v141 offset:32768
	ds_read_b128 v[178:181], v141 offset:33792
	ds_read_b128 v[182:185], v141 offset:34816
	ds_read_b128 v[186:189], v141 offset:35840
	ds_read_b128 v[190:193], v141 offset:36864
	ds_read_b128 v[200:203], v141 offset:37888
	ds_read_b128 v[204:207], v141 offset:38912
	ds_read_b128 v[208:211], v141 offset:39936
	global_load_lds_dwordx4 v136, s[36:37]
	s_mov_b32 m0, s67
	s_nop 0
	global_load_lds_dwordx4 v134, s[36:37]
	s_waitcnt vmcnt(8)
	s_waitcnt lgkmcnt(0)
	s_barrier
	v_mfma_f32_16x16x32_bf16 v[128:131], v[142:145], v[174:177], v[128:131]
	v_mfma_f32_16x16x32_bf16 v[124:127], v[150:153], v[174:177], v[124:127]
	v_mfma_f32_16x16x32_bf16 v[120:123], v[142:145], v[182:185], v[120:123]
	v_mfma_f32_16x16x32_bf16 v[112:115], v[150:153], v[182:185], v[112:115]
	v_mfma_f32_16x16x32_bf16 v[104:107], v[142:145], v[190:193], v[104:107]
	v_mfma_f32_16x16x32_bf16 v[96:99], v[150:153], v[190:193], v[96:99]
	v_mfma_f32_16x16x32_bf16 v[88:91], v[142:145], v[204:207], v[88:91]
	v_mfma_f32_16x16x32_bf16 v[80:83], v[150:153], v[204:207], v[80:83]
	v_mfma_f32_16x16x32_bf16 v[128:131], v[146:149], v[178:181], v[128:131]
	v_mfma_f32_16x16x32_bf16 v[124:127], v[154:157], v[178:181], v[124:127]
	v_mfma_f32_16x16x32_bf16 v[120:123], v[146:149], v[186:189], v[120:123]
	v_mfma_f32_16x16x32_bf16 v[112:115], v[154:157], v[186:189], v[112:115]
	v_mfma_f32_16x16x32_bf16 v[104:107], v[146:149], v[200:203], v[104:107]
	v_mfma_f32_16x16x32_bf16 v[96:99], v[154:157], v[200:203], v[96:99]
	v_mfma_f32_16x16x32_bf16 v[88:91], v[146:149], v[208:211], v[88:91]
	v_mfma_f32_16x16x32_bf16 v[80:83], v[154:157], v[208:211], v[80:83]
	v_mfma_f32_16x16x32_bf16 v[116:119], v[158:161], v[174:177], v[116:119]
	v_mfma_f32_16x16x32_bf16 v[108:111], v[166:169], v[174:177], v[108:111]
	v_mfma_f32_16x16x32_bf16 v[100:103], v[158:161], v[182:185], v[100:103]
	v_mfma_f32_16x16x32_bf16 v[92:95], v[166:169], v[182:185], v[92:95]
	v_mfma_f32_16x16x32_bf16 v[84:87], v[158:161], v[190:193], v[84:87]
	v_mfma_f32_16x16x32_bf16 v[76:79], v[166:169], v[190:193], v[76:79]
	v_mfma_f32_16x16x32_bf16 v[72:75], v[158:161], v[204:207], v[72:75]
	v_mfma_f32_16x16x32_bf16 v[68:71], v[166:169], v[204:207], v[68:71]
	v_mfma_f32_16x16x32_bf16 v[116:119], v[162:165], v[178:181], v[116:119]
	v_mfma_f32_16x16x32_bf16 v[108:111], v[170:173], v[178:181], v[108:111]
	v_mfma_f32_16x16x32_bf16 v[100:103], v[162:165], v[186:189], v[100:103]
	v_mfma_f32_16x16x32_bf16 v[92:95], v[170:173], v[186:189], v[92:95]
	v_mfma_f32_16x16x32_bf16 v[84:87], v[162:165], v[200:203], v[84:87]
	v_mfma_f32_16x16x32_bf16 v[76:79], v[170:173], v[200:203], v[76:79]
	v_mfma_f32_16x16x32_bf16 v[72:75], v[162:165], v[208:211], v[72:75]
	v_mfma_f32_16x16x32_bf16 v[68:71], v[170:173], v[208:211], v[68:71]
	s_barrier
	s_add_u32 s36, s96, 0x40000
	s_addc_u32 s37, s97, 0
	s_add_i32 s74, s74, s58
	s_mov_b32 m0, s74
	ds_read_b128 v[174:177], v141 offset:49152
	ds_read_b128 v[178:181], v141 offset:50176
	ds_read_b128 v[182:185], v141 offset:51200
	ds_read_b128 v[186:189], v141 offset:52224
	ds_read_b128 v[190:193], v141 offset:53248
	ds_read_b128 v[200:203], v141 offset:54272
	ds_read_b128 v[204:207], v141 offset:55296
	ds_read_b128 v[208:211], v141 offset:56320
	global_load_lds_dwordx4 v2, s[36:37]
	s_add_i32 m0, s74, 0x2000
	s_nop 0
	global_load_lds_dwordx4 v132, s[36:37]
	s_add_u32 s36, s96, 0x44000
	s_addc_u32 s37, s97, 0
	s_add_i32 s74, s75, s58
	s_mov_b32 m0, s74
	s_nop 0
	global_load_lds_dwordx4 v2, s[36:37]
	s_add_i32 m0, s74, 0x2000
	s_nop 0
	global_load_lds_dwordx4 v132, s[36:37]
	s_mov_b32 m0, s70
	s_nop 0
	global_load_lds_dwordx4 v136, s[94:95]
	s_mov_b32 m0, s71
	s_nop 0
	global_load_lds_dwordx4 v134, s[94:95]
	s_waitcnt vmcnt(8)
	s_waitcnt lgkmcnt(0)
	s_nop 0
	s_barrier
	v_mfma_f32_16x16x32_bf16 v[64:67], v[142:145], v[174:177], v[64:67]
	v_mfma_f32_16x16x32_bf16 v[60:63], v[150:153], v[174:177], v[60:63]
	v_mfma_f32_16x16x32_bf16 v[56:59], v[142:145], v[182:185], v[56:59]
	v_mfma_f32_16x16x32_bf16 v[48:51], v[150:153], v[182:185], v[48:51]
	v_mfma_f32_16x16x32_bf16 v[40:43], v[142:145], v[190:193], v[40:43]
	v_mfma_f32_16x16x32_bf16 v[32:35], v[150:153], v[190:193], v[32:35]
	v_mfma_f32_16x16x32_bf16 v[24:27], v[142:145], v[204:207], v[24:27]
	v_mfma_f32_16x16x32_bf16 v[16:19], v[150:153], v[204:207], v[16:19]
	v_mfma_f32_16x16x32_bf16 v[64:67], v[146:149], v[178:181], v[64:67]
	v_mfma_f32_16x16x32_bf16 v[60:63], v[154:157], v[178:181], v[60:63]
	v_mfma_f32_16x16x32_bf16 v[56:59], v[146:149], v[186:189], v[56:59]
	v_mfma_f32_16x16x32_bf16 v[48:51], v[154:157], v[186:189], v[48:51]
	v_mfma_f32_16x16x32_bf16 v[40:43], v[146:149], v[200:203], v[40:43]
	v_mfma_f32_16x16x32_bf16 v[32:35], v[154:157], v[200:203], v[32:35]
	v_mfma_f32_16x16x32_bf16 v[24:27], v[146:149], v[208:211], v[24:27]
	v_mfma_f32_16x16x32_bf16 v[16:19], v[154:157], v[208:211], v[16:19]
	v_mfma_f32_16x16x32_bf16 v[52:55], v[158:161], v[174:177], v[52:55]
	v_mfma_f32_16x16x32_bf16 v[44:47], v[166:169], v[174:177], v[44:47]
	v_mfma_f32_16x16x32_bf16 v[36:39], v[158:161], v[182:185], v[36:39]
	v_mfma_f32_16x16x32_bf16 v[28:31], v[166:169], v[182:185], v[28:31]
	v_mfma_f32_16x16x32_bf16 v[20:23], v[158:161], v[190:193], v[20:23]
	v_mfma_f32_16x16x32_bf16 v[12:15], v[166:169], v[190:193], v[12:15]
	v_mfma_f32_16x16x32_bf16 v[8:11], v[158:161], v[204:207], v[8:11]
	v_mfma_f32_16x16x32_bf16 v[4:7], v[166:169], v[204:207], v[4:7]
	v_mfma_f32_16x16x32_bf16 v[52:55], v[162:165], v[178:181], v[52:55]
	v_mfma_f32_16x16x32_bf16 v[44:47], v[170:173], v[178:181], v[44:47]
	v_mfma_f32_16x16x32_bf16 v[36:39], v[162:165], v[186:189], v[36:39]
	v_mfma_f32_16x16x32_bf16 v[28:31], v[170:173], v[186:189], v[28:31]
	v_mfma_f32_16x16x32_bf16 v[20:23], v[162:165], v[200:203], v[20:23]
	v_mfma_f32_16x16x32_bf16 v[12:15], v[170:173], v[200:203], v[12:15]
	v_mfma_f32_16x16x32_bf16 v[8:11], v[162:165], v[208:211], v[8:11]
	v_mfma_f32_16x16x32_bf16 v[4:7], v[170:173], v[208:211], v[4:7]
	s_barrier
	s_cmp_lg_u32 s82, 0
	s_mov_b32 s82, s40
	s_cbranch_scc1 .LBB0_939

.LBB0_1211:
	s_add_u32 s28, s26, 0x1fc000
	s_addc_u32 s29, s27, 0
	s_cmp_eq_u32 s58, 28
	s_cselect_b32 s36, s34, s28
	s_cselect_b32 s37, s19, s29
	s_cselect_b32 s31, s15, s49
	s_cselect_b32 s30, s35, s48
	s_add_u32 s28, s36, 0x200000
	s_addc_u32 s29, s37, 0
	s_add_i32 s59, 0, 0x10000
	s_add_i32 s61, 0, 0x14000
	ds_read_b128 v[68:71], v191
	ds_read_b128 v[72:75], v191 offset:1024
	ds_read_b128 v[76:79], v191 offset:2048
	ds_read_b128 v[80:83], v191 offset:3072
	ds_read_b128 v[148:151], v191 offset:16384
	ds_read_b128 v[152:155], v191 offset:17408
	ds_read_b128 v[156:159], v191 offset:18432
	ds_read_b128 v[160:163], v191 offset:19456
	s_add_i32 m0, s73, 0xc000
	ds_read_b128 v[164:167], v193
	ds_read_b128 v[178:181], v193 offset:1024
	ds_read_b128 v[182:185], v193 offset:2048
	ds_read_b128 v[186:189], v193 offset:3072
	ds_read_b128 v[200:203], v193 offset:4096
	ds_read_b128 v[204:207], v193 offset:5120
	ds_read_b128 v[208:211], v193 offset:6144
	ds_read_b128 v[222:225], v193 offset:7168
	global_load_lds_dwordx4 v174, s[26:27]
	s_add_i32 m0, s73, 0xe000
	s_nop 0
	global_load_lds_dwordx4 v176, s[26:27]
	s_waitcnt vmcnt(8)
	s_waitcnt lgkmcnt(0)
	s_nop 0
	s_barrier
	v_mfma_f32_16x16x32_bf16 v[144:147], v[68:71], v[164:167], v[144:147]
	v_mfma_f32_16x16x32_bf16 v[140:143], v[76:79], v[164:167], v[140:143]
	v_mfma_f32_16x16x32_bf16 v[136:139], v[68:71], v[182:185], v[136:139]
	v_mfma_f32_16x16x32_bf16 v[128:131], v[76:79], v[182:185], v[128:131]
	v_mfma_f32_16x16x32_bf16 v[112:115], v[68:71], v[200:203], v[112:115]
	v_mfma_f32_16x16x32_bf16 v[108:111], v[76:79], v[200:203], v[108:111]
	v_mfma_f32_16x16x32_bf16 v[104:107], v[68:71], v[208:211], v[104:107]
	v_mfma_f32_16x16x32_bf16 v[96:99], v[76:79], v[208:211], v[96:99]
	v_mfma_f32_16x16x32_bf16 v[144:147], v[72:75], v[178:181], v[144:147]
	v_mfma_f32_16x16x32_bf16 v[140:143], v[80:83], v[178:181], v[140:143]
	v_mfma_f32_16x16x32_bf16 v[136:139], v[72:75], v[186:189], v[136:139]
	v_mfma_f32_16x16x32_bf16 v[128:131], v[80:83], v[186:189], v[128:131]
	v_mfma_f32_16x16x32_bf16 v[112:115], v[72:75], v[204:207], v[112:115]
	v_mfma_f32_16x16x32_bf16 v[108:111], v[80:83], v[204:207], v[108:111]
	v_mfma_f32_16x16x32_bf16 v[104:107], v[72:75], v[222:225], v[104:107]
	v_mfma_f32_16x16x32_bf16 v[96:99], v[80:83], v[222:225], v[96:99]
	v_mfma_f32_16x16x32_bf16 v[132:135], v[148:151], v[164:167], v[132:135]
	v_mfma_f32_16x16x32_bf16 v[124:127], v[156:159], v[164:167], v[124:127]
	v_mfma_f32_16x16x32_bf16 v[120:123], v[148:151], v[182:185], v[120:123]
	v_mfma_f32_16x16x32_bf16 v[116:119], v[156:159], v[182:185], v[116:119]
	v_mfma_f32_16x16x32_bf16 v[100:103], v[148:151], v[200:203], v[100:103]
	v_mfma_f32_16x16x32_bf16 v[92:95], v[156:159], v[200:203], v[92:95]
	v_mfma_f32_16x16x32_bf16 v[88:91], v[148:151], v[208:211], v[88:91]
	v_mfma_f32_16x16x32_bf16 v[84:87], v[156:159], v[208:211], v[84:87]
	v_mfma_f32_16x16x32_bf16 v[132:135], v[152:155], v[178:181], v[132:135]
	v_mfma_f32_16x16x32_bf16 v[124:127], v[160:163], v[178:181], v[124:127]
	v_mfma_f32_16x16x32_bf16 v[120:123], v[152:155], v[186:189], v[120:123]
	v_mfma_f32_16x16x32_bf16 v[116:119], v[160:163], v[186:189], v[116:119]
	v_mfma_f32_16x16x32_bf16 v[100:103], v[152:155], v[204:207], v[100:103]
	v_mfma_f32_16x16x32_bf16 v[92:95], v[160:163], v[204:207], v[92:95]
	v_mfma_f32_16x16x32_bf16 v[88:91], v[152:155], v[222:225], v[88:91]
	v_mfma_f32_16x16x32_bf16 v[84:87], v[160:163], v[222:225], v[84:87]
	s_barrier
	s_add_i32 s59, s59, s72
	s_mov_b32 m0, s59
	ds_read_b128 v[164:167], v193 offset:16384
	ds_read_b128 v[178:181], v193 offset:17408
	ds_read_b128 v[182:185], v193 offset:18432
	ds_read_b128 v[186:189], v193 offset:19456
	ds_read_b128 v[200:203], v193 offset:20480
	ds_read_b128 v[204:207], v193 offset:21504
	ds_read_b128 v[208:211], v193 offset:22528
	ds_read_b128 v[222:225], v193 offset:23552
	global_load_lds_dwordx4 v2, s[30:31]
	s_add_i32 m0, s59, 0x2000
	s_add_u32 s66, s30, 0x4000
	s_addc_u32 s67, s31, 0
	s_add_i32 s59, s61, s72
	global_load_lds_dwordx4 v172, s[30:31]
	s_mov_b32 m0, s59
	s_nop 0
	global_load_lds_dwordx4 v2, s[66:67]
	s_add_i32 m0, s59, 0x2000
	s_nop 0
	global_load_lds_dwordx4 v172, s[66:67]
	s_mov_b32 m0, s73
	s_nop 0
	global_load_lds_dwordx4 v168, s[36:37]
	s_mov_b32 m0, s74
	s_nop 0
	global_load_lds_dwordx4 v170, s[36:37]
	s_waitcnt vmcnt(8)
	s_waitcnt lgkmcnt(0)
	s_nop 0
	s_barrier
	v_mfma_f32_16x16x32_bf16 v[64:67], v[68:71], v[164:167], v[64:67]
	v_mfma_f32_16x16x32_bf16 v[60:63], v[76:79], v[164:167], v[60:63]
	v_mfma_f32_16x16x32_bf16 v[48:51], v[68:71], v[182:185], v[48:51]
	v_mfma_f32_16x16x32_bf16 v[44:47], v[76:79], v[182:185], v[44:47]
	v_mfma_f32_16x16x32_bf16 v[32:35], v[68:71], v[200:203], v[32:35]
	v_mfma_f32_16x16x32_bf16 v[28:31], v[76:79], v[200:203], v[28:31]
	v_mfma_f32_16x16x32_bf16 v[16:19], v[68:71], v[208:211], v[16:19]
	v_mfma_f32_16x16x32_bf16 v[12:15], v[76:79], v[208:211], v[12:15]
	v_mfma_f32_16x16x32_bf16 v[64:67], v[72:75], v[178:181], v[64:67]
	v_mfma_f32_16x16x32_bf16 v[60:63], v[80:83], v[178:181], v[60:63]
	v_mfma_f32_16x16x32_bf16 v[48:51], v[72:75], v[186:189], v[48:51]
	v_mfma_f32_16x16x32_bf16 v[44:47], v[80:83], v[186:189], v[44:47]
	v_mfma_f32_16x16x32_bf16 v[32:35], v[72:75], v[204:207], v[32:35]
	v_mfma_f32_16x16x32_bf16 v[28:31], v[80:83], v[204:207], v[28:31]
	v_mfma_f32_16x16x32_bf16 v[16:19], v[72:75], v[222:225], v[16:19]
	v_mfma_f32_16x16x32_bf16 v[12:15], v[80:83], v[222:225], v[12:15]
	v_mfma_f32_16x16x32_bf16 v[56:59], v[148:151], v[164:167], v[56:59]
	v_mfma_f32_16x16x32_bf16 v[52:55], v[156:159], v[164:167], v[52:55]
	v_mfma_f32_16x16x32_bf16 v[40:43], v[148:151], v[182:185], v[40:43]
	v_mfma_f32_16x16x32_bf16 v[36:39], v[156:159], v[182:185], v[36:39]
	v_mfma_f32_16x16x32_bf16 v[24:27], v[148:151], v[200:203], v[24:27]
	v_mfma_f32_16x16x32_bf16 v[20:23], v[156:159], v[200:203], v[20:23]
	v_mfma_f32_16x16x32_bf16 v[8:11], v[148:151], v[208:211], v[8:11]
	v_mfma_f32_16x16x32_bf16 v[4:7], v[156:159], v[208:211], v[4:7]
	v_mfma_f32_16x16x32_bf16 v[56:59], v[152:155], v[178:181], v[56:59]
	v_mfma_f32_16x16x32_bf16 v[52:55], v[160:163], v[178:181], v[52:55]
	v_mfma_f32_16x16x32_bf16 v[40:43], v[152:155], v[186:189], v[40:43]
	v_mfma_f32_16x16x32_bf16 v[36:39], v[160:163], v[186:189], v[36:39]
	v_mfma_f32_16x16x32_bf16 v[24:27], v[152:155], v[204:207], v[24:27]
	v_mfma_f32_16x16x32_bf16 v[20:23], v[160:163], v[204:207], v[20:23]
	v_mfma_f32_16x16x32_bf16 v[8:11], v[152:155], v[222:225], v[8:11]
	v_mfma_f32_16x16x32_bf16 v[4:7], v[160:163], v[222:225], v[4:7]
	s_barrier
	s_add_i32 s59, 0, 0x18000
	s_add_i32 s61, 0, 0x1c000
	ds_read_b128 v[68:71], v191 offset:32768
	ds_read_b128 v[72:75], v191 offset:33792
	ds_read_b128 v[76:79], v191 offset:34816
	ds_read_b128 v[80:83], v191 offset:35840
	ds_read_b128 v[148:151], v191 offset:49152
	ds_read_b128 v[152:155], v191 offset:50176
	ds_read_b128 v[156:159], v191 offset:51200
	ds_read_b128 v[160:163], v191 offset:52224
	s_add_u32 s36, s36, 0x4000
	s_addc_u32 s37, s37, 0
	s_mov_b32 m0, s75
	ds_read_b128 v[164:167], v193 offset:32768
	ds_read_b128 v[178:181], v193 offset:33792
	ds_read_b128 v[182:185], v193 offset:34816
	ds_read_b128 v[186:189], v193 offset:35840
	ds_read_b128 v[200:203], v193 offset:36864
	ds_read_b128 v[204:207], v193 offset:37888
	ds_read_b128 v[208:211], v193 offset:38912
	ds_read_b128 v[222:225], v193 offset:39936
	global_load_lds_dwordx4 v168, s[36:37]
	s_mov_b32 m0, s76
	s_nop 0
	global_load_lds_dwordx4 v170, s[36:37]
	s_waitcnt vmcnt(8)
	s_waitcnt lgkmcnt(0)
	s_barrier
	v_mfma_f32_16x16x32_bf16 v[144:147], v[68:71], v[164:167], v[144:147]
	v_mfma_f32_16x16x32_bf16 v[140:143], v[76:79], v[164:167], v[140:143]
	v_mfma_f32_16x16x32_bf16 v[136:139], v[68:71], v[182:185], v[136:139]
	v_mfma_f32_16x16x32_bf16 v[128:131], v[76:79], v[182:185], v[128:131]
	v_mfma_f32_16x16x32_bf16 v[112:115], v[68:71], v[200:203], v[112:115]
	v_mfma_f32_16x16x32_bf16 v[108:111], v[76:79], v[200:203], v[108:111]
	v_mfma_f32_16x16x32_bf16 v[104:107], v[68:71], v[208:211], v[104:107]
	v_mfma_f32_16x16x32_bf16 v[96:99], v[76:79], v[208:211], v[96:99]
	v_mfma_f32_16x16x32_bf16 v[144:147], v[72:75], v[178:181], v[144:147]
	v_mfma_f32_16x16x32_bf16 v[140:143], v[80:83], v[178:181], v[140:143]
	v_mfma_f32_16x16x32_bf16 v[136:139], v[72:75], v[186:189], v[136:139]
	v_mfma_f32_16x16x32_bf16 v[128:131], v[80:83], v[186:189], v[128:131]
	v_mfma_f32_16x16x32_bf16 v[112:115], v[72:75], v[204:207], v[112:115]
	v_mfma_f32_16x16x32_bf16 v[108:111], v[80:83], v[204:207], v[108:111]
	v_mfma_f32_16x16x32_bf16 v[104:107], v[72:75], v[222:225], v[104:107]
	v_mfma_f32_16x16x32_bf16 v[96:99], v[80:83], v[222:225], v[96:99]
	v_mfma_f32_16x16x32_bf16 v[132:135], v[148:151], v[164:167], v[132:135]
	v_mfma_f32_16x16x32_bf16 v[124:127], v[156:159], v[164:167], v[124:127]
	v_mfma_f32_16x16x32_bf16 v[120:123], v[148:151], v[182:185], v[120:123]
	v_mfma_f32_16x16x32_bf16 v[116:119], v[156:159], v[182:185], v[116:119]
	v_mfma_f32_16x16x32_bf16 v[100:103], v[148:151], v[200:203], v[100:103]
	v_mfma_f32_16x16x32_bf16 v[92:95], v[156:159], v[200:203], v[92:95]
	v_mfma_f32_16x16x32_bf16 v[88:91], v[148:151], v[208:211], v[88:91]
	v_mfma_f32_16x16x32_bf16 v[84:87], v[156:159], v[208:211], v[84:87]
	v_mfma_f32_16x16x32_bf16 v[132:135], v[152:155], v[178:181], v[132:135]
	v_mfma_f32_16x16x32_bf16 v[124:127], v[160:163], v[178:181], v[124:127]
	v_mfma_f32_16x16x32_bf16 v[120:123], v[152:155], v[186:189], v[120:123]
	v_mfma_f32_16x16x32_bf16 v[116:119], v[160:163], v[186:189], v[116:119]
	v_mfma_f32_16x16x32_bf16 v[100:103], v[152:155], v[204:207], v[100:103]
	v_mfma_f32_16x16x32_bf16 v[92:95], v[160:163], v[204:207], v[92:95]
	v_mfma_f32_16x16x32_bf16 v[88:91], v[152:155], v[222:225], v[88:91]
	v_mfma_f32_16x16x32_bf16 v[84:87], v[160:163], v[222:225], v[84:87]
	s_barrier
	s_add_u32 s36, s30, 0x40000
	s_addc_u32 s37, s31, 0
	s_add_i32 s59, s59, s72
	s_mov_b32 m0, s59
	ds_read_b128 v[164:167], v193 offset:49152
	ds_read_b128 v[178:181], v193 offset:50176
	ds_read_b128 v[182:185], v193 offset:51200
	ds_read_b128 v[186:189], v193 offset:52224
	ds_read_b128 v[200:203], v193 offset:53248
	ds_read_b128 v[204:207], v193 offset:54272
	ds_read_b128 v[208:211], v193 offset:55296
	ds_read_b128 v[222:225], v193 offset:56320
	global_load_lds_dwordx4 v2, s[36:37]
	s_add_i32 m0, s59, 0x2000
	s_add_u32 s30, s30, 0x44000
	s_addc_u32 s31, s31, 0
	global_load_lds_dwordx4 v172, s[36:37]
	s_add_i32 s36, s61, s72
	s_mov_b32 m0, s36
	s_nop 0
	global_load_lds_dwordx4 v2, s[30:31]
	s_add_i32 m0, s36, 0x2000
	s_nop 0
	global_load_lds_dwordx4 v172, s[30:31]
	s_mov_b32 m0, s79
	s_nop 0
	global_load_lds_dwordx4 v168, s[28:29]
	s_mov_b32 m0, s82
	s_nop 0
	global_load_lds_dwordx4 v170, s[28:29]
	s_waitcnt vmcnt(8)
	s_waitcnt lgkmcnt(0)
	s_barrier
	v_mfma_f32_16x16x32_bf16 v[64:67], v[68:71], v[164:167], v[64:67]
	v_mfma_f32_16x16x32_bf16 v[60:63], v[76:79], v[164:167], v[60:63]
	v_mfma_f32_16x16x32_bf16 v[48:51], v[68:71], v[182:185], v[48:51]
	v_mfma_f32_16x16x32_bf16 v[44:47], v[76:79], v[182:185], v[44:47]
	v_mfma_f32_16x16x32_bf16 v[32:35], v[68:71], v[200:203], v[32:35]
	v_mfma_f32_16x16x32_bf16 v[28:31], v[76:79], v[200:203], v[28:31]
	v_mfma_f32_16x16x32_bf16 v[16:19], v[68:71], v[208:211], v[16:19]
	v_mfma_f32_16x16x32_bf16 v[12:15], v[76:79], v[208:211], v[12:15]
	v_mfma_f32_16x16x32_bf16 v[64:67], v[72:75], v[178:181], v[64:67]
	v_mfma_f32_16x16x32_bf16 v[60:63], v[80:83], v[178:181], v[60:63]
	v_mfma_f32_16x16x32_bf16 v[48:51], v[72:75], v[186:189], v[48:51]
	v_mfma_f32_16x16x32_bf16 v[44:47], v[80:83], v[186:189], v[44:47]
	v_mfma_f32_16x16x32_bf16 v[32:35], v[72:75], v[204:207], v[32:35]
	v_mfma_f32_16x16x32_bf16 v[28:31], v[80:83], v[204:207], v[28:31]
	v_mfma_f32_16x16x32_bf16 v[16:19], v[72:75], v[222:225], v[16:19]
	v_mfma_f32_16x16x32_bf16 v[12:15], v[80:83], v[222:225], v[12:15]
	v_mfma_f32_16x16x32_bf16 v[56:59], v[148:151], v[164:167], v[56:59]
	v_mfma_f32_16x16x32_bf16 v[52:55], v[156:159], v[164:167], v[52:55]
	v_mfma_f32_16x16x32_bf16 v[40:43], v[148:151], v[182:185], v[40:43]
	v_mfma_f32_16x16x32_bf16 v[36:39], v[156:159], v[182:185], v[36:39]
	v_mfma_f32_16x16x32_bf16 v[24:27], v[148:151], v[200:203], v[24:27]
	v_mfma_f32_16x16x32_bf16 v[20:23], v[156:159], v[200:203], v[20:23]
	v_mfma_f32_16x16x32_bf16 v[8:11], v[148:151], v[208:211], v[8:11]
	v_mfma_f32_16x16x32_bf16 v[4:7], v[156:159], v[208:211], v[4:7]
	v_mfma_f32_16x16x32_bf16 v[56:59], v[152:155], v[178:181], v[56:59]
	v_mfma_f32_16x16x32_bf16 v[52:55], v[160:163], v[178:181], v[52:55]
	v_mfma_f32_16x16x32_bf16 v[40:43], v[152:155], v[186:189], v[40:43]
	v_mfma_f32_16x16x32_bf16 v[36:39], v[160:163], v[186:189], v[36:39]
	v_mfma_f32_16x16x32_bf16 v[24:27], v[152:155], v[204:207], v[24:27]
	v_mfma_f32_16x16x32_bf16 v[20:23], v[160:163], v[204:207], v[20:23]
	v_mfma_f32_16x16x32_bf16 v[8:11], v[152:155], v[222:225], v[8:11]
	v_mfma_f32_16x16x32_bf16 v[4:7], v[160:163], v[222:225], v[4:7]
	s_barrier
	s_add_i32 s58, s58, 2
	s_add_u32 s48, s48, 0x80000
	s_addc_u32 s49, s49, 0
	s_add_u32 s26, s26, 0x400000
	s_addc_u32 s27, s27, 0
	s_cmp_gt_u32 s58, 29
	s_cbranch_scc0 .LBB0_1211
	s_and_b64 vcc, exec, s[10:11]
	s_cbranch_vccz .LBB0_1214
	s_barrier
